# all six K-loops: LDS-DMA in saddr form (64-bit address VALU removed), relaxed-wait select blocks replaced by plain vmcnt(8), on top of the MMA-path trim
# speedup vs baseline: 1.0021x; 1.0021x over previous
; #define PG8_STAGE(bufoff, gbase, voff) do { _Pragma("unroll") for (int _i = 0; _i < 2; ++_i) \
;         __builtin_amdgcn_global_load_lds((const unsigned*)((const char*)(gbase) + (voff)[_i]), (PG8_LAS unsigned*)(lds + (bufoff) + ldsw + _i * 8192), 16, 0, 0); } while (0)
; #define PG8_LDA(dst, b, h) do { _Pragma("unroll") for (int m = 0; m < 4; ++m) _Pragma("unroll") for (int k = 0; k < 2; ++k) dst[m][k] = *(const PG8_LAS bf16x8*)(lds + PG8_SA(b, h) + aoff + m * 2048 + k * 1024); } while (0)
; #define PG8_LDB(dst, b, h) do { _Pragma("unroll") for (int n = 0; n < 2; ++n) _Pragma("unroll") for (int k = 0; k < 2; ++k) dst[n][k] = *(const PG8_LAS bf16x8*)(lds + PG8_SB(b, h) + boff + n * 2048 + k * 1024); } while (0)
; #define PG8_WAIT_L(n) asm volatile("s_waitcnt lgkmcnt(" #n ")" ::: "memory")
; #define PG8_WAIT_V_SEL(sel) asm volatile("s_cmp_eq_u32 %0, 0\n\ts_cbranch_scc1 .Lw8_%=\n\ts_waitcnt vmcnt(22)\n\ts_branch .Lwd_%=\n.Lw8_%=:\n\ts_waitcnt vmcnt(8)\n.Lwd_%=:" :: "s"(sel) : "memory", "scc")
; #define PG8_BAR __builtin_amdgcn_s_barrier()
; #define PG8_SCHED __builtin_amdgcn_sched_barrier(0)
;     ...
;             PG8_LDB(B0, 0, 0); PG8_LDB(B1, 0, 1); PG8_SCHED; PG8_LDA(At, 0, 0); PG8_STAGE(PG8_SA(1, 1), a1 + hstep, voffA);
;             PG8_WAIT_V_SEL(relax);
;             PG8_WAIT_L(0); PG8_BAR; PG8_MMA(0, 0, At, B0); PG8_MMA(0, 1, At, B1); PG8_BAR; PG8_SCHED;
;             PG8_LDA(At, 0, 1); PG8_STAGE(PG8_SB(0, 0), b2, voffB); PG8_STAGE(PG8_SB(0, 1), b2 + hstep, voffB); PG8_STAGE(PG8_SA(0, 0), a2, voffA);
;             PG8_WAIT_V_SEL(relax);
;             PG8_WAIT_L(0); PG8_BAR; PG8_MMA(1, 0, At, B0); PG8_MMA(1, 1, At, B1); PG8_BAR; PG8_SCHED;
.LBB0_234:
	s_add_u32 s0, s78, 0xfff80080
	s_addc_u32 s1, s79, -1
	s_add_i32 s40, 0, 0x10000
	s_cmp_eq_u32 s37, 28
	s_cselect_b32 s83, s19, s1
	s_cselect_b32 s82, s20, s0
	s_cselect_b32 s81, s24, s35
	s_cselect_b32 s80, s31, s33
	s_add_i32 s41, 0, 0x14000
	v_add_u32_e32 v154, s40, v181
	v_add_u32_e32 v166, s41, v181
	ds_read_b128 v[142:145], v154
	ds_read_b128 v[146:149], v154 offset:1024
	ds_read_b128 v[150:153], v154 offset:2048
	ds_read_b128 v[154:157], v154 offset:3072
	ds_read_b128 v[158:161], v166
	ds_read_b128 v[162:165], v166 offset:1024
	ds_read_b128 v[174:177], v166 offset:2048
	ds_read_b128 v[188:191], v166 offset:3072
	s_add_i32 m0, s75, 0xc000
	ds_read_b128 v[198:201], v196
	ds_read_b128 v[202:205], v196 offset:1024
	ds_read_b128 v[206:209], v196 offset:2048
	ds_read_b128 v[210:213], v196 offset:3072
	ds_read_b128 v[214:217], v196 offset:4096
	ds_read_b128 v[218:221], v196 offset:5120
	ds_read_b128 v[222:225], v196 offset:6144
	ds_read_b128 v[226:229], v196 offset:7168
	global_load_lds_dwordx4 v138, s[78:79]
	s_add_i32 m0, s75, 0xe000
	s_nop 0
	global_load_lds_dwordx4 v140, s[78:79]
	s_waitcnt vmcnt(8)
	s_waitcnt lgkmcnt(0)
	s_setprio 1
	s_barrier
	v_mfma_f32_16x16x32_bf16 v[126:129], v[142:145], v[198:201], v[126:129]
	v_mfma_f32_16x16x32_bf16 v[110:113], v[150:153], v[198:201], v[110:113]
	v_mfma_f32_16x16x32_bf16 v[122:125], v[142:145], v[206:209], v[122:125]
	v_mfma_f32_16x16x32_bf16 v[106:109], v[150:153], v[206:209], v[106:109]
	v_mfma_f32_16x16x32_bf16 v[118:121], v[142:145], v[214:217], v[118:121]
	v_mfma_f32_16x16x32_bf16 v[102:105], v[150:153], v[214:217], v[102:105]
	v_mfma_f32_16x16x32_bf16 v[114:117], v[142:145], v[222:225], v[114:117]
	v_mfma_f32_16x16x32_bf16 v[98:101], v[150:153], v[222:225], v[98:101]
	v_mfma_f32_16x16x32_bf16 v[126:129], v[146:149], v[202:205], v[126:129]
	v_mfma_f32_16x16x32_bf16 v[110:113], v[154:157], v[202:205], v[110:113]
	v_mfma_f32_16x16x32_bf16 v[122:125], v[146:149], v[210:213], v[122:125]
	v_mfma_f32_16x16x32_bf16 v[106:109], v[154:157], v[210:213], v[106:109]
	v_mfma_f32_16x16x32_bf16 v[118:121], v[146:149], v[218:221], v[118:121]
	v_mfma_f32_16x16x32_bf16 v[102:105], v[154:157], v[218:221], v[102:105]
	v_mfma_f32_16x16x32_bf16 v[114:117], v[146:149], v[226:229], v[114:117]
	v_mfma_f32_16x16x32_bf16 v[98:101], v[154:157], v[226:229], v[98:101]
	v_mfma_f32_16x16x32_bf16 v[82:85], v[158:161], v[198:201], v[82:85]
	v_mfma_f32_16x16x32_bf16 v[30:33], v[174:177], v[198:201], v[30:33]
	v_mfma_f32_16x16x32_bf16 v[70:73], v[158:161], v[206:209], v[70:73]
	v_mfma_f32_16x16x32_bf16 v[26:29], v[174:177], v[206:209], v[26:29]
	v_mfma_f32_16x16x32_bf16 v[66:69], v[158:161], v[214:217], v[66:69]
	v_mfma_f32_16x16x32_bf16 v[22:25], v[174:177], v[214:217], v[22:25]
	v_mfma_f32_16x16x32_bf16 v[58:61], v[158:161], v[222:225], v[58:61]
	v_mfma_f32_16x16x32_bf16 v[18:21], v[174:177], v[222:225], v[18:21]
	v_mfma_f32_16x16x32_bf16 v[82:85], v[162:165], v[202:205], v[82:85]
	v_mfma_f32_16x16x32_bf16 v[30:33], v[188:191], v[202:205], v[30:33]
	v_mfma_f32_16x16x32_bf16 v[70:73], v[162:165], v[210:213], v[70:73]
	v_mfma_f32_16x16x32_bf16 v[26:29], v[188:191], v[210:213], v[26:29]
	v_mfma_f32_16x16x32_bf16 v[66:69], v[162:165], v[218:221], v[66:69]
	v_mfma_f32_16x16x32_bf16 v[22:25], v[188:191], v[218:221], v[22:25]
	v_mfma_f32_16x16x32_bf16 v[58:61], v[162:165], v[226:229], v[58:61]
	v_mfma_f32_16x16x32_bf16 v[18:21], v[188:191], v[226:229], v[18:21]
	s_barrier
	s_setprio 0
	s_add_i32 s0, s40, s87
	s_mov_b32 m0, s0
	ds_read_b128 v[198:201], v196 offset:16384
	ds_read_b128 v[202:205], v196 offset:17408
	ds_read_b128 v[206:209], v196 offset:18432
	ds_read_b128 v[210:213], v196 offset:19456
	ds_read_b128 v[214:217], v196 offset:20480
	ds_read_b128 v[218:221], v196 offset:21504
	ds_read_b128 v[222:225], v196 offset:22528
	ds_read_b128 v[226:229], v196 offset:23552
	global_load_lds_dwordx4 v182, s[80:81]
	s_add_i32 m0, s0, 0x2000
	s_add_u32 s0, s80, 0x80000
	s_addc_u32 s1, s81, 0
	s_add_i32 s40, s41, s87
	global_load_lds_dwordx4 v134, s[80:81]
	s_mov_b32 m0, s40
	s_nop 0
	global_load_lds_dwordx4 v182, s[0:1]
	s_add_i32 m0, s40, 0x2000
	s_nop 0
	global_load_lds_dwordx4 v134, s[0:1]
	s_mov_b32 m0, s75
	s_nop 0
	global_load_lds_dwordx4 v130, s[82:83]
	s_mov_b32 m0, s88
	s_nop 0
	global_load_lds_dwordx4 v132, s[82:83]
	s_waitcnt vmcnt(8)
	s_waitcnt lgkmcnt(0)
	s_setprio 1
	s_barrier
	v_mfma_f32_16x16x32_bf16 v[94:97], v[142:145], v[198:201], v[94:97]
	v_mfma_f32_16x16x32_bf16 v[74:77], v[150:153], v[198:201], v[74:77]
	v_mfma_f32_16x16x32_bf16 v[90:93], v[142:145], v[206:209], v[90:93]
	v_mfma_f32_16x16x32_bf16 v[62:65], v[150:153], v[206:209], v[62:65]
	v_mfma_f32_16x16x32_bf16 v[86:89], v[142:145], v[214:217], v[86:89]
	v_mfma_f32_16x16x32_bf16 v[54:57], v[150:153], v[214:217], v[54:57]
	v_mfma_f32_16x16x32_bf16 v[78:81], v[142:145], v[222:225], v[78:81]
	v_mfma_f32_16x16x32_bf16 v[50:53], v[150:153], v[222:225], v[50:53]
	v_mfma_f32_16x16x32_bf16 v[94:97], v[146:149], v[202:205], v[94:97]
	v_mfma_f32_16x16x32_bf16 v[74:77], v[154:157], v[202:205], v[74:77]
	v_mfma_f32_16x16x32_bf16 v[90:93], v[146:149], v[210:213], v[90:93]
	v_mfma_f32_16x16x32_bf16 v[62:65], v[154:157], v[210:213], v[62:65]
	v_mfma_f32_16x16x32_bf16 v[86:89], v[146:149], v[218:221], v[86:89]
	v_mfma_f32_16x16x32_bf16 v[54:57], v[154:157], v[218:221], v[54:57]
	v_mfma_f32_16x16x32_bf16 v[78:81], v[146:149], v[226:229], v[78:81]
	v_mfma_f32_16x16x32_bf16 v[50:53], v[154:157], v[226:229], v[50:53]
	v_mfma_f32_16x16x32_bf16 v[46:49], v[158:161], v[198:201], v[46:49]
	v_mfma_f32_16x16x32_bf16 v[14:17], v[174:177], v[198:201], v[14:17]
	v_mfma_f32_16x16x32_bf16 v[42:45], v[158:161], v[206:209], v[42:45]
	v_mfma_f32_16x16x32_bf16 v[10:13], v[174:177], v[206:209], v[10:13]
	v_mfma_f32_16x16x32_bf16 v[38:41], v[158:161], v[214:217], v[38:41]
	v_mfma_f32_16x16x32_bf16 v[6:9], v[174:177], v[214:217], v[6:9]
	v_mfma_f32_16x16x32_bf16 v[34:37], v[158:161], v[222:225], v[34:37]
	v_mfma_f32_16x16x32_bf16 v[2:5], v[174:177], v[222:225], v[2:5]
	v_mfma_f32_16x16x32_bf16 v[46:49], v[162:165], v[202:205], v[46:49]
	v_mfma_f32_16x16x32_bf16 v[14:17], v[188:191], v[202:205], v[14:17]
	v_mfma_f32_16x16x32_bf16 v[42:45], v[162:165], v[210:213], v[42:45]
	v_mfma_f32_16x16x32_bf16 v[10:13], v[188:191], v[210:213], v[10:13]
	v_mfma_f32_16x16x32_bf16 v[38:41], v[162:165], v[218:221], v[38:41]
	v_mfma_f32_16x16x32_bf16 v[6:9], v[188:191], v[218:221], v[6:9]
	v_mfma_f32_16x16x32_bf16 v[34:37], v[162:165], v[226:229], v[34:37]
	v_mfma_f32_16x16x32_bf16 v[2:5], v[188:191], v[226:229], v[2:5]
	s_barrier
; #define PG8_STAGE(bufoff, gbase, voff) do { _Pragma("unroll") for (int _i = 0; _i < 2; ++_i) \
;         __builtin_amdgcn_global_load_lds((const unsigned*)((const char*)(gbase) + (voff)[_i]), (PG8_LAS unsigned*)(lds + (bufoff) + ldsw + _i * 8192), 16, 0, 0); } while (0)
; #define PG8_LDA(dst, b, h) do { _Pragma("unroll") for (int m = 0; m < 4; ++m) _Pragma("unroll") for (int k = 0; k < 2; ++k) dst[m][k] = *(const PG8_LAS bf16x8*)(lds + PG8_SA(b, h) + aoff + m * 2048 + k * 1024); } while (0)
; #define PG8_LDB(dst, b, h) do { _Pragma("unroll") for (int n = 0; n < 2; ++n) _Pragma("unroll") for (int k = 0; k < 2; ++k) dst[n][k] = *(const PG8_LAS bf16x8*)(lds + PG8_SB(b, h) + boff + n * 2048 + k * 1024); } while (0)
; #define PG8_WAIT_V(n) asm volatile("s_waitcnt vmcnt(" #n ")" ::: "memory")
; #define PG8_WAIT_L(n) asm volatile("s_waitcnt lgkmcnt(" #n ")" ::: "memory")
; #define PG8_BAR __builtin_amdgcn_s_barrier()
; #define PG8_SCHED __builtin_amdgcn_sched_barrier(0)
;     ...
;             PG8_LDB(B0, 1, 0); PG8_LDB(B1, 1, 1); PG8_SCHED; PG8_LDA(At, 1, 0); PG8_STAGE(PG8_SA(0, 1), a2 + hstep, voffA);
;             PG8_WAIT_V(8); PG8_WAIT_L(0); PG8_BAR; PG8_MMA(0, 0, At, B0); PG8_MMA(0, 1, At, B1); PG8_BAR; PG8_SCHED;
;             PG8_LDA(At, 1, 1); PG8_STAGE(PG8_SB(1, 0), b3, voffB); PG8_STAGE(PG8_SB(1, 1), b3 + hstep, voffB); PG8_STAGE(PG8_SA(1, 0), a3, voffA);
;             PG8_WAIT_V(8); PG8_WAIT_L(0); PG8_BAR; PG8_MMA(1, 0, At, B0); PG8_MMA(1, 1, At, B1); PG8_BAR; PG8_SCHED;
	s_setprio 0
	s_add_i32 s40, 0, 0x18000
	s_add_i32 s41, 0, 0x1c000
	v_add_u32_e32 v154, s40, v181
	v_add_u32_e32 v166, s41, v181
	ds_read_b128 v[142:145], v154
	ds_read_b128 v[146:149], v154 offset:1024
	ds_read_b128 v[150:153], v154 offset:2048
	ds_read_b128 v[154:157], v154 offset:3072
	ds_read_b128 v[158:161], v166
	ds_read_b128 v[162:165], v166 offset:1024
	ds_read_b128 v[174:177], v166 offset:2048
	ds_read_b128 v[188:191], v166 offset:3072
	s_add_u32 s0, s82, 0x80000
	s_addc_u32 s1, s83, 0
	s_mov_b32 m0, s89
	ds_read_b128 v[198:201], v196 offset:32768
	ds_read_b128 v[202:205], v196 offset:33792
	ds_read_b128 v[206:209], v196 offset:34816
	ds_read_b128 v[210:213], v196 offset:35840
	ds_read_b128 v[214:217], v196 offset:36864
	ds_read_b128 v[218:221], v196 offset:37888
	ds_read_b128 v[222:225], v196 offset:38912
	ds_read_b128 v[226:229], v196 offset:39936
	global_load_lds_dwordx4 v130, s[0:1]
	s_mov_b32 m0, s90
	s_nop 0
	global_load_lds_dwordx4 v132, s[0:1]
	s_waitcnt vmcnt(8)
	s_waitcnt lgkmcnt(0)
	s_setprio 1
	s_barrier
	v_mfma_f32_16x16x32_bf16 v[126:129], v[142:145], v[198:201], v[126:129]
	v_mfma_f32_16x16x32_bf16 v[110:113], v[150:153], v[198:201], v[110:113]
	v_mfma_f32_16x16x32_bf16 v[122:125], v[142:145], v[206:209], v[122:125]
	v_mfma_f32_16x16x32_bf16 v[106:109], v[150:153], v[206:209], v[106:109]
	v_mfma_f32_16x16x32_bf16 v[118:121], v[142:145], v[214:217], v[118:121]
	v_mfma_f32_16x16x32_bf16 v[102:105], v[150:153], v[214:217], v[102:105]
	v_mfma_f32_16x16x32_bf16 v[114:117], v[142:145], v[222:225], v[114:117]
	v_mfma_f32_16x16x32_bf16 v[98:101], v[150:153], v[222:225], v[98:101]
	v_mfma_f32_16x16x32_bf16 v[126:129], v[146:149], v[202:205], v[126:129]
	v_mfma_f32_16x16x32_bf16 v[110:113], v[154:157], v[202:205], v[110:113]
	v_mfma_f32_16x16x32_bf16 v[122:125], v[146:149], v[210:213], v[122:125]
	v_mfma_f32_16x16x32_bf16 v[106:109], v[154:157], v[210:213], v[106:109]
	v_mfma_f32_16x16x32_bf16 v[118:121], v[146:149], v[218:221], v[118:121]
	v_mfma_f32_16x16x32_bf16 v[102:105], v[154:157], v[218:221], v[102:105]
	v_mfma_f32_16x16x32_bf16 v[114:117], v[146:149], v[226:229], v[114:117]
	v_mfma_f32_16x16x32_bf16 v[98:101], v[154:157], v[226:229], v[98:101]
	v_mfma_f32_16x16x32_bf16 v[82:85], v[158:161], v[198:201], v[82:85]
	v_mfma_f32_16x16x32_bf16 v[30:33], v[174:177], v[198:201], v[30:33]
	v_mfma_f32_16x16x32_bf16 v[70:73], v[158:161], v[206:209], v[70:73]
	v_mfma_f32_16x16x32_bf16 v[26:29], v[174:177], v[206:209], v[26:29]
	v_mfma_f32_16x16x32_bf16 v[66:69], v[158:161], v[214:217], v[66:69]
	v_mfma_f32_16x16x32_bf16 v[22:25], v[174:177], v[214:217], v[22:25]
	v_mfma_f32_16x16x32_bf16 v[58:61], v[158:161], v[222:225], v[58:61]
	v_mfma_f32_16x16x32_bf16 v[18:21], v[174:177], v[222:225], v[18:21]
	v_mfma_f32_16x16x32_bf16 v[82:85], v[162:165], v[202:205], v[82:85]
	v_mfma_f32_16x16x32_bf16 v[30:33], v[188:191], v[202:205], v[30:33]
	v_mfma_f32_16x16x32_bf16 v[70:73], v[162:165], v[210:213], v[70:73]
	v_mfma_f32_16x16x32_bf16 v[26:29], v[188:191], v[210:213], v[26:29]
	v_mfma_f32_16x16x32_bf16 v[66:69], v[162:165], v[218:221], v[66:69]
	v_mfma_f32_16x16x32_bf16 v[22:25], v[188:191], v[218:221], v[22:25]
	v_mfma_f32_16x16x32_bf16 v[58:61], v[162:165], v[226:229], v[58:61]
	v_mfma_f32_16x16x32_bf16 v[18:21], v[188:191], v[226:229], v[18:21]
	s_barrier
	s_setprio 0
	s_add_i32 s0, s40, s87
	s_mov_b32 m0, s0
	ds_read_b128 v[198:201], v196 offset:49152
	ds_read_b128 v[202:205], v196 offset:50176
	ds_read_b128 v[206:209], v196 offset:51200
	ds_read_b128 v[210:213], v196 offset:52224
	ds_read_b128 v[214:217], v196 offset:53248
	ds_read_b128 v[218:221], v196 offset:54272
	ds_read_b128 v[222:225], v196 offset:55296
	ds_read_b128 v[226:229], v196 offset:56320
	s_add_u32 s100, s80, 0x80
	s_addc_u32 s101, s81, 0
	global_load_lds_dwordx4 v182, s[100:101]
	s_add_i32 m0, s0, 0x2000
	s_add_u32 s0, s80, 0x80080
	s_addc_u32 s1, s81, 0
	s_add_i32 s40, s41, s87
	global_load_lds_dwordx4 v134, s[100:101]
	s_mov_b32 m0, s40
	s_nop 0
	global_load_lds_dwordx4 v182, s[0:1]
	s_add_i32 m0, s40, 0x2000
	s_nop 0
	global_load_lds_dwordx4 v134, s[0:1]
	s_mov_b32 m0, s94
	s_nop 0
	s_add_u32 s100, s82, 0x80
	s_addc_u32 s101, s83, 0
	global_load_lds_dwordx4 v130, s[100:101]
	s_mov_b32 m0, s95
	s_nop 0
	global_load_lds_dwordx4 v132, s[100:101]
	s_waitcnt vmcnt(8)
	s_waitcnt lgkmcnt(0)
	s_setprio 1
	s_barrier
	v_mfma_f32_16x16x32_bf16 v[94:97], v[142:145], v[198:201], v[94:97]
	v_mfma_f32_16x16x32_bf16 v[74:77], v[150:153], v[198:201], v[74:77]
	v_mfma_f32_16x16x32_bf16 v[90:93], v[142:145], v[206:209], v[90:93]
	v_mfma_f32_16x16x32_bf16 v[62:65], v[150:153], v[206:209], v[62:65]
	v_mfma_f32_16x16x32_bf16 v[86:89], v[142:145], v[214:217], v[86:89]
	v_mfma_f32_16x16x32_bf16 v[54:57], v[150:153], v[214:217], v[54:57]
	v_mfma_f32_16x16x32_bf16 v[78:81], v[142:145], v[222:225], v[78:81]
	v_mfma_f32_16x16x32_bf16 v[50:53], v[150:153], v[222:225], v[50:53]
	v_mfma_f32_16x16x32_bf16 v[94:97], v[146:149], v[202:205], v[94:97]
	v_mfma_f32_16x16x32_bf16 v[74:77], v[154:157], v[202:205], v[74:77]
	v_mfma_f32_16x16x32_bf16 v[90:93], v[146:149], v[210:213], v[90:93]
	v_mfma_f32_16x16x32_bf16 v[62:65], v[154:157], v[210:213], v[62:65]
	v_mfma_f32_16x16x32_bf16 v[86:89], v[146:149], v[218:221], v[86:89]
	v_mfma_f32_16x16x32_bf16 v[54:57], v[154:157], v[218:221], v[54:57]
	v_mfma_f32_16x16x32_bf16 v[78:81], v[146:149], v[226:229], v[78:81]
	v_mfma_f32_16x16x32_bf16 v[50:53], v[154:157], v[226:229], v[50:53]
	v_mfma_f32_16x16x32_bf16 v[46:49], v[158:161], v[198:201], v[46:49]
	v_mfma_f32_16x16x32_bf16 v[14:17], v[174:177], v[198:201], v[14:17]
	v_mfma_f32_16x16x32_bf16 v[42:45], v[158:161], v[206:209], v[42:45]
	v_mfma_f32_16x16x32_bf16 v[10:13], v[174:177], v[206:209], v[10:13]
	v_mfma_f32_16x16x32_bf16 v[38:41], v[158:161], v[214:217], v[38:41]
	v_mfma_f32_16x16x32_bf16 v[6:9], v[174:177], v[214:217], v[6:9]
	v_mfma_f32_16x16x32_bf16 v[34:37], v[158:161], v[222:225], v[34:37]
	v_mfma_f32_16x16x32_bf16 v[2:5], v[174:177], v[222:225], v[2:5]
	v_mfma_f32_16x16x32_bf16 v[46:49], v[162:165], v[202:205], v[46:49]
	v_mfma_f32_16x16x32_bf16 v[14:17], v[188:191], v[202:205], v[14:17]
	v_mfma_f32_16x16x32_bf16 v[42:45], v[162:165], v[210:213], v[42:45]
	v_mfma_f32_16x16x32_bf16 v[10:13], v[188:191], v[210:213], v[10:13]
	v_mfma_f32_16x16x32_bf16 v[38:41], v[162:165], v[218:221], v[38:41]
	v_mfma_f32_16x16x32_bf16 v[6:9], v[188:191], v[218:221], v[6:9]
	v_mfma_f32_16x16x32_bf16 v[34:37], v[162:165], v[226:229], v[34:37]
	v_mfma_f32_16x16x32_bf16 v[2:5], v[188:191], v[226:229], v[2:5]
	s_barrier
	s_setprio 0
	s_add_i32 s37, s37, 2
	s_add_u32 s78, s78, 0x100
	s_addc_u32 s79, s79, 0
	s_add_u32 s33, s33, 0x100
	s_addc_u32 s35, s35, 0
	s_cmp_gt_u32 s37, 29
	s_cbranch_scc0 .LBB0_234
	s_and_b64 vcc, exec, s[64:65]
	s_cbranch_vccz .LBB0_237
	s_barrier

; #define PG8_STAGE(bufoff, gbase, voff) do { _Pragma("unroll") for (int _i = 0; _i < 2; ++_i) \
;         __builtin_amdgcn_global_load_lds((const unsigned*)((const char*)(gbase) + (voff)[_i]), (PG8_LAS unsigned*)(lds + (bufoff) + ldsw + _i * 8192), 16, 0, 0); } while (0)
; #define PG8_LDA(dst, b, h) do { _Pragma("unroll") for (int m = 0; m < 4; ++m) _Pragma("unroll") for (int k = 0; k < 2; ++k) dst[m][k] = *(const PG8_LAS bf16x8*)(lds + PG8_SA(b, h) + aoff + m * 2048 + k * 1024); } while (0)
; #define PG8_LDB(dst, b, h) do { _Pragma("unroll") for (int n = 0; n < 2; ++n) _Pragma("unroll") for (int k = 0; k < 2; ++k) dst[n][k] = *(const PG8_LAS bf16x8*)(lds + PG8_SB(b, h) + boff + n * 2048 + k * 1024); } while (0)
; #define PG8_WAIT_L(n) asm volatile("s_waitcnt lgkmcnt(" #n ")" ::: "memory")
; #define PG8_WAIT_V_SEL(sel) asm volatile("s_cmp_eq_u32 %0, 0\n\ts_cbranch_scc1 .Lw8_%=\n\ts_waitcnt vmcnt(22)\n\ts_branch .Lwd_%=\n.Lw8_%=:\n\ts_waitcnt vmcnt(8)\n.Lwd_%=:" :: "s"(sel) : "memory", "scc")
; #define PG8_BAR __builtin_amdgcn_s_barrier()
; #define PG8_SCHED __builtin_amdgcn_sched_barrier(0)
;     ...
;             PG8_LDB(B0, 0, 0); PG8_LDB(B1, 0, 1); PG8_SCHED; PG8_LDA(At, 0, 0); PG8_STAGE(PG8_SA(1, 1), a1 + hstep, voffA);
;             PG8_WAIT_V_SEL(relax);
;             PG8_WAIT_L(0); PG8_BAR; PG8_MMA(0, 0, At, B0); PG8_MMA(0, 1, At, B1); PG8_BAR; PG8_SCHED;
;             PG8_LDA(At, 0, 1); PG8_STAGE(PG8_SB(0, 0), b2, voffB); PG8_STAGE(PG8_SB(0, 1), b2 + hstep, voffB); PG8_STAGE(PG8_SA(0, 0), a2, voffA);
;             PG8_WAIT_V_SEL(relax);
;             PG8_WAIT_L(0); PG8_BAR; PG8_MMA(1, 0, At, B0); PG8_MMA(1, 1, At, B1); PG8_BAR; PG8_SCHED;
.LBB0_541:
	s_add_u32 s0, s82, 0xfff80080
	s_addc_u32 s1, s83, -1
	s_add_i32 s79, 0, 0x10000
	s_cmp_eq_u32 s73, 28
	s_cselect_b32 s87, s40, s1
	s_cselect_b32 s86, s41, s0
	s_cselect_b32 s85, s57, s71
	s_cselect_b32 s84, s58, s59
	s_add_i32 s81, 0, 0x14000
	v_add_u32_e32 v102, s79, v227
	v_add_u32_e32 v158, s81, v227
	ds_read_b128 v[90:93], v102
	ds_read_b128 v[94:97], v102 offset:1024
	ds_read_b128 v[98:101], v102 offset:2048
	ds_read_b128 v[102:105], v102 offset:3072
	ds_read_b128 v[146:149], v158
	ds_read_b128 v[150:153], v158 offset:1024
	ds_read_b128 v[154:157], v158 offset:2048
	ds_read_b128 v[158:161], v158 offset:3072
	s_add_i32 m0, s44, 0xc000
	ds_read_b128 v[162:165], v230
	ds_read_b128 v[166:169], v230 offset:1024
	ds_read_b128 v[184:187], v230 offset:2048
	ds_read_b128 v[190:193], v230 offset:3072
	ds_read_b128 v[194:197], v230 offset:4096
	ds_read_b128 v[198:201], v230 offset:5120
	ds_read_b128 v[202:205], v230 offset:6144
	ds_read_b128 v[206:209], v230 offset:7168
	global_load_lds_dwordx4 v180, s[82:83]
	s_add_i32 m0, s44, 0xe000
	s_nop 0
	global_load_lds_dwordx4 v188, s[82:83]
	s_waitcnt vmcnt(8)
	s_waitcnt lgkmcnt(0)
	s_setprio 1
	s_barrier
	v_mfma_f32_16x16x32_bf16 v[142:145], v[90:93], v[162:165], v[142:145]
	v_mfma_f32_16x16x32_bf16 v[138:141], v[98:101], v[162:165], v[138:141]
	v_mfma_f32_16x16x32_bf16 v[126:129], v[90:93], v[184:187], v[126:129]
	v_mfma_f32_16x16x32_bf16 v[122:125], v[98:101], v[184:187], v[122:125]
	v_mfma_f32_16x16x32_bf16 v[110:113], v[90:93], v[194:197], v[110:113]
	v_mfma_f32_16x16x32_bf16 v[106:109], v[98:101], v[194:197], v[106:109]
	v_mfma_f32_16x16x32_bf16 v[78:81], v[90:93], v[202:205], v[78:81]
	v_mfma_f32_16x16x32_bf16 v[74:77], v[98:101], v[202:205], v[74:77]
	v_mfma_f32_16x16x32_bf16 v[142:145], v[94:97], v[166:169], v[142:145]
	v_mfma_f32_16x16x32_bf16 v[138:141], v[102:105], v[166:169], v[138:141]
	v_mfma_f32_16x16x32_bf16 v[126:129], v[94:97], v[190:193], v[126:129]
	v_mfma_f32_16x16x32_bf16 v[122:125], v[102:105], v[190:193], v[122:125]
	v_mfma_f32_16x16x32_bf16 v[110:113], v[94:97], v[198:201], v[110:113]
	v_mfma_f32_16x16x32_bf16 v[106:109], v[102:105], v[198:201], v[106:109]
	v_mfma_f32_16x16x32_bf16 v[78:81], v[94:97], v[206:209], v[78:81]
	v_mfma_f32_16x16x32_bf16 v[74:77], v[102:105], v[206:209], v[74:77]
	v_mfma_f32_16x16x32_bf16 v[134:137], v[146:149], v[162:165], v[134:137]
	v_mfma_f32_16x16x32_bf16 v[130:133], v[154:157], v[162:165], v[130:133]
	v_mfma_f32_16x16x32_bf16 v[118:121], v[146:149], v[184:187], v[118:121]
	v_mfma_f32_16x16x32_bf16 v[114:117], v[154:157], v[184:187], v[114:117]
	v_mfma_f32_16x16x32_bf16 v[86:89], v[146:149], v[194:197], v[86:89]
	v_mfma_f32_16x16x32_bf16 v[82:85], v[154:157], v[194:197], v[82:85]
	v_mfma_f32_16x16x32_bf16 v[70:73], v[146:149], v[202:205], v[70:73]
	v_mfma_f32_16x16x32_bf16 v[66:69], v[154:157], v[202:205], v[66:69]
	v_mfma_f32_16x16x32_bf16 v[134:137], v[150:153], v[166:169], v[134:137]
	v_mfma_f32_16x16x32_bf16 v[130:133], v[158:161], v[166:169], v[130:133]
	v_mfma_f32_16x16x32_bf16 v[118:121], v[150:153], v[190:193], v[118:121]
	v_mfma_f32_16x16x32_bf16 v[114:117], v[158:161], v[190:193], v[114:117]
	v_mfma_f32_16x16x32_bf16 v[86:89], v[150:153], v[198:201], v[86:89]
	v_mfma_f32_16x16x32_bf16 v[82:85], v[158:161], v[198:201], v[82:85]
	v_mfma_f32_16x16x32_bf16 v[70:73], v[150:153], v[206:209], v[70:73]
	v_mfma_f32_16x16x32_bf16 v[66:69], v[158:161], v[206:209], v[66:69]
	s_barrier
	s_setprio 0
	s_add_i32 s0, s79, s30
	s_mov_b32 m0, s0
	ds_read_b128 v[162:165], v230 offset:16384
	ds_read_b128 v[166:169], v230 offset:17408
	ds_read_b128 v[184:187], v230 offset:18432
	ds_read_b128 v[190:193], v230 offset:19456
	ds_read_b128 v[194:197], v230 offset:20480
	ds_read_b128 v[198:201], v230 offset:21504
	ds_read_b128 v[202:205], v230 offset:22528
	ds_read_b128 v[206:209], v230 offset:23552
	global_load_lds_dwordx4 v182, s[84:85]
	s_add_i32 m0, s0, 0x2000
	s_add_u32 s0, s84, 0x80000
	s_addc_u32 s1, s85, 0
	s_add_i32 s79, s81, s30
	global_load_lds_dwordx4 v178, s[84:85]
	s_mov_b32 m0, s79
	s_nop 0
	global_load_lds_dwordx4 v182, s[0:1]
	s_add_i32 m0, s79, 0x2000
	s_nop 0
	global_load_lds_dwordx4 v178, s[0:1]
	s_mov_b32 m0, s44
	s_nop 0
	global_load_lds_dwordx4 v174, s[86:87]
	s_mov_b32 m0, s45
	s_nop 0
	global_load_lds_dwordx4 v176, s[86:87]
	s_waitcnt vmcnt(8)
	s_waitcnt lgkmcnt(0)
	s_setprio 1
	s_barrier
	v_mfma_f32_16x16x32_bf16 v[62:65], v[90:93], v[162:165], v[62:65]
	v_mfma_f32_16x16x32_bf16 v[58:61], v[98:101], v[162:165], v[58:61]
	v_mfma_f32_16x16x32_bf16 v[46:49], v[90:93], v[184:187], v[46:49]
	v_mfma_f32_16x16x32_bf16 v[42:45], v[98:101], v[184:187], v[42:45]
	v_mfma_f32_16x16x32_bf16 v[30:33], v[90:93], v[194:197], v[30:33]
	v_mfma_f32_16x16x32_bf16 v[26:29], v[98:101], v[194:197], v[26:29]
	v_mfma_f32_16x16x32_bf16 v[14:17], v[90:93], v[202:205], v[14:17]
	v_mfma_f32_16x16x32_bf16 v[10:13], v[98:101], v[202:205], v[10:13]
	v_mfma_f32_16x16x32_bf16 v[62:65], v[94:97], v[166:169], v[62:65]
	v_mfma_f32_16x16x32_bf16 v[58:61], v[102:105], v[166:169], v[58:61]
	v_mfma_f32_16x16x32_bf16 v[46:49], v[94:97], v[190:193], v[46:49]
	v_mfma_f32_16x16x32_bf16 v[42:45], v[102:105], v[190:193], v[42:45]
	v_mfma_f32_16x16x32_bf16 v[30:33], v[94:97], v[198:201], v[30:33]
	v_mfma_f32_16x16x32_bf16 v[26:29], v[102:105], v[198:201], v[26:29]
	v_mfma_f32_16x16x32_bf16 v[14:17], v[94:97], v[206:209], v[14:17]
	v_mfma_f32_16x16x32_bf16 v[10:13], v[102:105], v[206:209], v[10:13]
	v_mfma_f32_16x16x32_bf16 v[54:57], v[146:149], v[162:165], v[54:57]
	v_mfma_f32_16x16x32_bf16 v[50:53], v[154:157], v[162:165], v[50:53]
	v_mfma_f32_16x16x32_bf16 v[38:41], v[146:149], v[184:187], v[38:41]
	v_mfma_f32_16x16x32_bf16 v[34:37], v[154:157], v[184:187], v[34:37]
	v_mfma_f32_16x16x32_bf16 v[22:25], v[146:149], v[194:197], v[22:25]
	v_mfma_f32_16x16x32_bf16 v[18:21], v[154:157], v[194:197], v[18:21]
	v_mfma_f32_16x16x32_bf16 v[6:9], v[146:149], v[202:205], v[6:9]
	v_mfma_f32_16x16x32_bf16 v[2:5], v[154:157], v[202:205], v[2:5]
	v_mfma_f32_16x16x32_bf16 v[54:57], v[150:153], v[166:169], v[54:57]
	v_mfma_f32_16x16x32_bf16 v[50:53], v[158:161], v[166:169], v[50:53]
	v_mfma_f32_16x16x32_bf16 v[38:41], v[150:153], v[190:193], v[38:41]
	v_mfma_f32_16x16x32_bf16 v[34:37], v[158:161], v[190:193], v[34:37]
	v_mfma_f32_16x16x32_bf16 v[22:25], v[150:153], v[198:201], v[22:25]
	v_mfma_f32_16x16x32_bf16 v[18:21], v[158:161], v[198:201], v[18:21]
	v_mfma_f32_16x16x32_bf16 v[6:9], v[150:153], v[206:209], v[6:9]
	v_mfma_f32_16x16x32_bf16 v[2:5], v[158:161], v[206:209], v[2:5]
	s_barrier
; #define PG8_STAGE(bufoff, gbase, voff) do { _Pragma("unroll") for (int _i = 0; _i < 2; ++_i) \
;         __builtin_amdgcn_global_load_lds((const unsigned*)((const char*)(gbase) + (voff)[_i]), (PG8_LAS unsigned*)(lds + (bufoff) + ldsw + _i * 8192), 16, 0, 0); } while (0)
; #define PG8_LDA(dst, b, h) do { _Pragma("unroll") for (int m = 0; m < 4; ++m) _Pragma("unroll") for (int k = 0; k < 2; ++k) dst[m][k] = *(const PG8_LAS bf16x8*)(lds + PG8_SA(b, h) + aoff + m * 2048 + k * 1024); } while (0)
; #define PG8_LDB(dst, b, h) do { _Pragma("unroll") for (int n = 0; n < 2; ++n) _Pragma("unroll") for (int k = 0; k < 2; ++k) dst[n][k] = *(const PG8_LAS bf16x8*)(lds + PG8_SB(b, h) + boff + n * 2048 + k * 1024); } while (0)
; #define PG8_WAIT_V(n) asm volatile("s_waitcnt vmcnt(" #n ")" ::: "memory")
; #define PG8_WAIT_L(n) asm volatile("s_waitcnt lgkmcnt(" #n ")" ::: "memory")
; #define PG8_BAR __builtin_amdgcn_s_barrier()
; #define PG8_SCHED __builtin_amdgcn_sched_barrier(0)
;     ...
;             PG8_LDB(B0, 1, 0); PG8_LDB(B1, 1, 1); PG8_SCHED; PG8_LDA(At, 1, 0); PG8_STAGE(PG8_SA(0, 1), a2 + hstep, voffA);
;             PG8_WAIT_V(8); PG8_WAIT_L(0); PG8_BAR; PG8_MMA(0, 0, At, B0); PG8_MMA(0, 1, At, B1); PG8_BAR; PG8_SCHED;
;             PG8_LDA(At, 1, 1); PG8_STAGE(PG8_SB(1, 0), b3, voffB); PG8_STAGE(PG8_SB(1, 1), b3 + hstep, voffB); PG8_STAGE(PG8_SA(1, 0), a3, voffA);
;             PG8_WAIT_V(8); PG8_WAIT_L(0); PG8_BAR; PG8_MMA(1, 0, At, B0); PG8_MMA(1, 1, At, B1); PG8_BAR; PG8_SCHED;
	s_setprio 0
	s_add_i32 s79, 0, 0x18000
	s_add_i32 s81, 0, 0x1c000
	v_add_u32_e32 v102, s79, v227
	v_add_u32_e32 v158, s81, v227
	ds_read_b128 v[90:93], v102
	ds_read_b128 v[94:97], v102 offset:1024
	ds_read_b128 v[98:101], v102 offset:2048
	ds_read_b128 v[102:105], v102 offset:3072
	ds_read_b128 v[146:149], v158
	ds_read_b128 v[150:153], v158 offset:1024
	ds_read_b128 v[154:157], v158 offset:2048
	ds_read_b128 v[158:161], v158 offset:3072
	s_add_u32 s0, s86, 0x80000
	s_addc_u32 s1, s87, 0
	s_mov_b32 m0, s46
	ds_read_b128 v[162:165], v230 offset:32768
	ds_read_b128 v[166:169], v230 offset:33792
	ds_read_b128 v[184:187], v230 offset:34816
	ds_read_b128 v[190:193], v230 offset:35840
	ds_read_b128 v[194:197], v230 offset:36864
	ds_read_b128 v[198:201], v230 offset:37888
	ds_read_b128 v[202:205], v230 offset:38912
	ds_read_b128 v[206:209], v230 offset:39936
	global_load_lds_dwordx4 v174, s[0:1]
	s_mov_b32 m0, s47
	s_nop 0
	global_load_lds_dwordx4 v176, s[0:1]
	s_waitcnt vmcnt(8)
	s_waitcnt lgkmcnt(0)
	s_setprio 1
	s_barrier
	v_mfma_f32_16x16x32_bf16 v[142:145], v[90:93], v[162:165], v[142:145]
	v_mfma_f32_16x16x32_bf16 v[138:141], v[98:101], v[162:165], v[138:141]
	v_mfma_f32_16x16x32_bf16 v[126:129], v[90:93], v[184:187], v[126:129]
	v_mfma_f32_16x16x32_bf16 v[122:125], v[98:101], v[184:187], v[122:125]
	v_mfma_f32_16x16x32_bf16 v[110:113], v[90:93], v[194:197], v[110:113]
	v_mfma_f32_16x16x32_bf16 v[106:109], v[98:101], v[194:197], v[106:109]
	v_mfma_f32_16x16x32_bf16 v[78:81], v[90:93], v[202:205], v[78:81]
	v_mfma_f32_16x16x32_bf16 v[74:77], v[98:101], v[202:205], v[74:77]
	v_mfma_f32_16x16x32_bf16 v[142:145], v[94:97], v[166:169], v[142:145]
	v_mfma_f32_16x16x32_bf16 v[138:141], v[102:105], v[166:169], v[138:141]
	v_mfma_f32_16x16x32_bf16 v[126:129], v[94:97], v[190:193], v[126:129]
	v_mfma_f32_16x16x32_bf16 v[122:125], v[102:105], v[190:193], v[122:125]
	v_mfma_f32_16x16x32_bf16 v[110:113], v[94:97], v[198:201], v[110:113]
	v_mfma_f32_16x16x32_bf16 v[106:109], v[102:105], v[198:201], v[106:109]
	v_mfma_f32_16x16x32_bf16 v[78:81], v[94:97], v[206:209], v[78:81]
	v_mfma_f32_16x16x32_bf16 v[74:77], v[102:105], v[206:209], v[74:77]
	v_mfma_f32_16x16x32_bf16 v[134:137], v[146:149], v[162:165], v[134:137]
	v_mfma_f32_16x16x32_bf16 v[130:133], v[154:157], v[162:165], v[130:133]
	v_mfma_f32_16x16x32_bf16 v[118:121], v[146:149], v[184:187], v[118:121]
	v_mfma_f32_16x16x32_bf16 v[114:117], v[154:157], v[184:187], v[114:117]
	v_mfma_f32_16x16x32_bf16 v[86:89], v[146:149], v[194:197], v[86:89]
	v_mfma_f32_16x16x32_bf16 v[82:85], v[154:157], v[194:197], v[82:85]
	v_mfma_f32_16x16x32_bf16 v[70:73], v[146:149], v[202:205], v[70:73]
	v_mfma_f32_16x16x32_bf16 v[66:69], v[154:157], v[202:205], v[66:69]
	v_mfma_f32_16x16x32_bf16 v[134:137], v[150:153], v[166:169], v[134:137]
	v_mfma_f32_16x16x32_bf16 v[130:133], v[158:161], v[166:169], v[130:133]
	v_mfma_f32_16x16x32_bf16 v[118:121], v[150:153], v[190:193], v[118:121]
	v_mfma_f32_16x16x32_bf16 v[114:117], v[158:161], v[190:193], v[114:117]
	v_mfma_f32_16x16x32_bf16 v[86:89], v[150:153], v[198:201], v[86:89]
	v_mfma_f32_16x16x32_bf16 v[82:85], v[158:161], v[198:201], v[82:85]
	v_mfma_f32_16x16x32_bf16 v[70:73], v[150:153], v[206:209], v[70:73]
	v_mfma_f32_16x16x32_bf16 v[66:69], v[158:161], v[206:209], v[66:69]
	s_barrier
	s_setprio 0
	s_add_i32 s0, s79, s30
	s_mov_b32 m0, s0
	ds_read_b128 v[162:165], v230 offset:49152
	ds_read_b128 v[166:169], v230 offset:50176
	ds_read_b128 v[184:187], v230 offset:51200
	ds_read_b128 v[190:193], v230 offset:52224
	ds_read_b128 v[194:197], v230 offset:53248
	ds_read_b128 v[198:201], v230 offset:54272
	ds_read_b128 v[202:205], v230 offset:55296
	ds_read_b128 v[206:209], v230 offset:56320
	s_add_u32 s100, s84, 0x80
	s_addc_u32 s101, s85, 0
	global_load_lds_dwordx4 v182, s[100:101]
	s_add_i32 m0, s0, 0x2000
	s_add_u32 s0, s84, 0x80080
	s_addc_u32 s1, s85, 0
	s_add_i32 s79, s81, s30
	global_load_lds_dwordx4 v178, s[100:101]
	s_mov_b32 m0, s79
	s_nop 0
	global_load_lds_dwordx4 v182, s[0:1]
	s_add_i32 m0, s79, 0x2000
	s_nop 0
	global_load_lds_dwordx4 v178, s[0:1]
	s_mov_b32 m0, s49
	s_nop 0
	s_add_u32 s100, s86, 0x80
	s_addc_u32 s101, s87, 0
	global_load_lds_dwordx4 v174, s[100:101]
	s_mov_b32 m0, s50
	s_nop 0
	global_load_lds_dwordx4 v176, s[100:101]
	s_waitcnt vmcnt(8)
	s_waitcnt lgkmcnt(0)
	s_setprio 1
	s_barrier
	v_mfma_f32_16x16x32_bf16 v[62:65], v[90:93], v[162:165], v[62:65]
	v_mfma_f32_16x16x32_bf16 v[58:61], v[98:101], v[162:165], v[58:61]
	v_mfma_f32_16x16x32_bf16 v[46:49], v[90:93], v[184:187], v[46:49]
	v_mfma_f32_16x16x32_bf16 v[42:45], v[98:101], v[184:187], v[42:45]
	v_mfma_f32_16x16x32_bf16 v[30:33], v[90:93], v[194:197], v[30:33]
	v_mfma_f32_16x16x32_bf16 v[26:29], v[98:101], v[194:197], v[26:29]
	v_mfma_f32_16x16x32_bf16 v[14:17], v[90:93], v[202:205], v[14:17]
	v_mfma_f32_16x16x32_bf16 v[10:13], v[98:101], v[202:205], v[10:13]
	v_mfma_f32_16x16x32_bf16 v[62:65], v[94:97], v[166:169], v[62:65]
	v_mfma_f32_16x16x32_bf16 v[58:61], v[102:105], v[166:169], v[58:61]
	v_mfma_f32_16x16x32_bf16 v[46:49], v[94:97], v[190:193], v[46:49]
	v_mfma_f32_16x16x32_bf16 v[42:45], v[102:105], v[190:193], v[42:45]
	v_mfma_f32_16x16x32_bf16 v[30:33], v[94:97], v[198:201], v[30:33]
	v_mfma_f32_16x16x32_bf16 v[26:29], v[102:105], v[198:201], v[26:29]
	v_mfma_f32_16x16x32_bf16 v[14:17], v[94:97], v[206:209], v[14:17]
	v_mfma_f32_16x16x32_bf16 v[10:13], v[102:105], v[206:209], v[10:13]
	v_mfma_f32_16x16x32_bf16 v[54:57], v[146:149], v[162:165], v[54:57]
	v_mfma_f32_16x16x32_bf16 v[50:53], v[154:157], v[162:165], v[50:53]
	v_mfma_f32_16x16x32_bf16 v[38:41], v[146:149], v[184:187], v[38:41]
	v_mfma_f32_16x16x32_bf16 v[34:37], v[154:157], v[184:187], v[34:37]
	v_mfma_f32_16x16x32_bf16 v[22:25], v[146:149], v[194:197], v[22:25]
	v_mfma_f32_16x16x32_bf16 v[18:21], v[154:157], v[194:197], v[18:21]
	v_mfma_f32_16x16x32_bf16 v[6:9], v[146:149], v[202:205], v[6:9]
	v_mfma_f32_16x16x32_bf16 v[2:5], v[154:157], v[202:205], v[2:5]
	v_mfma_f32_16x16x32_bf16 v[54:57], v[150:153], v[166:169], v[54:57]
	v_mfma_f32_16x16x32_bf16 v[50:53], v[158:161], v[166:169], v[50:53]
	v_mfma_f32_16x16x32_bf16 v[38:41], v[150:153], v[190:193], v[38:41]
	v_mfma_f32_16x16x32_bf16 v[34:37], v[158:161], v[190:193], v[34:37]
	v_mfma_f32_16x16x32_bf16 v[22:25], v[150:153], v[198:201], v[22:25]
	v_mfma_f32_16x16x32_bf16 v[18:21], v[158:161], v[198:201], v[18:21]
	v_mfma_f32_16x16x32_bf16 v[6:9], v[150:153], v[206:209], v[6:9]
	v_mfma_f32_16x16x32_bf16 v[2:5], v[158:161], v[206:209], v[2:5]
	s_barrier
	s_setprio 0
	s_add_i32 s73, s73, 2
	s_add_u32 s82, s82, 0x100
	s_addc_u32 s83, s83, 0
	s_add_u32 s59, s59, 0x100
	s_addc_u32 s71, s71, 0
	s_cmp_gt_u32 s73, 29
	s_cbranch_scc0 .LBB0_541
	s_and_b64 vcc, exec, s[68:69]
	s_cbranch_vccz .LBB0_544
	s_barrier

; #define PG8_STAGE(bufoff, gbase, voff) do { _Pragma("unroll") for (int _i = 0; _i < 2; ++_i) \
;         __builtin_amdgcn_global_load_lds((const unsigned*)((const char*)(gbase) + (voff)[_i]), (PG8_LAS unsigned*)(lds + (bufoff) + ldsw + _i * 8192), 16, 0, 0); } while (0)
; #define PG8_LDA(dst, b, h) do { _Pragma("unroll") for (int m = 0; m < 4; ++m) _Pragma("unroll") for (int k = 0; k < 2; ++k) dst[m][k] = *(const PG8_LAS bf16x8*)(lds + PG8_SA(b, h) + aoff + m * 2048 + k * 1024); } while (0)
; #define PG8_LDB(dst, b, h) do { _Pragma("unroll") for (int n = 0; n < 2; ++n) _Pragma("unroll") for (int k = 0; k < 2; ++k) dst[n][k] = *(const PG8_LAS bf16x8*)(lds + PG8_SB(b, h) + boff + n * 2048 + k * 1024); } while (0)
; #define PG8_WAIT_L(n) asm volatile("s_waitcnt lgkmcnt(" #n ")" ::: "memory")
; #define PG8_WAIT_V_SEL(sel) asm volatile("s_cmp_eq_u32 %0, 0\n\ts_cbranch_scc1 .Lw8_%=\n\ts_waitcnt vmcnt(22)\n\ts_branch .Lwd_%=\n.Lw8_%=:\n\ts_waitcnt vmcnt(8)\n.Lwd_%=:" :: "s"(sel) : "memory", "scc")
; #define PG8_BAR __builtin_amdgcn_s_barrier()
; #define PG8_SCHED __builtin_amdgcn_sched_barrier(0)
;     ...
;             PG8_LDB(B0, 0, 0); PG8_LDB(B1, 0, 1); PG8_SCHED; PG8_LDA(At, 0, 0); PG8_STAGE(PG8_SA(1, 1), a1 + hstep, voffA);
;             PG8_WAIT_V_SEL(relax);
;             PG8_WAIT_L(0); PG8_BAR; PG8_MMA(0, 0, At, B0); PG8_MMA(0, 1, At, B1); PG8_BAR; PG8_SCHED;
;             PG8_LDA(At, 0, 1); PG8_STAGE(PG8_SB(0, 0), b2, voffB); PG8_STAGE(PG8_SB(0, 1), b2 + hstep, voffB); PG8_STAGE(PG8_SA(0, 0), a2, voffA);
;             PG8_WAIT_V_SEL(relax);
;             PG8_WAIT_L(0); PG8_BAR; PG8_MMA(1, 0, At, B0); PG8_MMA(1, 1, At, B1); PG8_BAR; PG8_SCHED;
.LBB0_596:
	s_add_u32 s0, s74, 0xfff80080
	s_addc_u32 s1, s75, -1
	s_add_i32 s83, 0, 0x10000
	s_cmp_eq_u32 s82, 28
	s_cselect_b32 s79, s40, s1
	s_cselect_b32 s78, s41, s0
	v_add_u32_e32 v149, s83, v146
	s_cselect_b32 s77, s65, s81
	s_cselect_b32 s76, s73, s80
	s_add_i32 s84, 0, 0x14000
	ds_read_b128 v[150:153], v149
	ds_read_b128 v[154:157], v149 offset:1024
	ds_read_b128 v[158:161], v149 offset:2048
	ds_read_b128 v[162:165], v149 offset:3072
	v_add_u32_e32 v149, s84, v146
	ds_read_b128 v[166:169], v149
	ds_read_b128 v[172:175], v149 offset:1024
	ds_read_b128 v[176:179], v149 offset:2048
	ds_read_b128 v[188:191], v149 offset:3072
	s_add_i32 m0, s35, 0xc000
	ds_read_b128 v[192:195], v148
	ds_read_b128 v[196:199], v148 offset:1024
	ds_read_b128 v[200:203], v148 offset:2048
	ds_read_b128 v[204:207], v148 offset:3072
	ds_read_b128 v[208:211], v148 offset:4096
	ds_read_b128 v[212:215], v148 offset:5120
	ds_read_b128 v[216:219], v148 offset:6144
	ds_read_b128 v[220:223], v148 offset:7168
	global_load_lds_dwordx4 v140, s[74:75]
	s_add_i32 m0, s35, 0xe000
	s_nop 0
	global_load_lds_dwordx4 v142, s[74:75]
	s_waitcnt vmcnt(8)
	s_waitcnt lgkmcnt(0)
	s_setprio 1
	s_barrier
	v_mfma_f32_16x16x32_bf16 v[126:129], v[150:153], v[192:195], v[126:129]
	v_mfma_f32_16x16x32_bf16 v[110:113], v[158:161], v[192:195], v[110:113]
	v_mfma_f32_16x16x32_bf16 v[122:125], v[150:153], v[200:203], v[122:125]
	v_mfma_f32_16x16x32_bf16 v[106:109], v[158:161], v[200:203], v[106:109]
	v_mfma_f32_16x16x32_bf16 v[118:121], v[150:153], v[208:211], v[118:121]
	v_mfma_f32_16x16x32_bf16 v[102:105], v[158:161], v[208:211], v[102:105]
	v_mfma_f32_16x16x32_bf16 v[114:117], v[150:153], v[216:219], v[114:117]
	v_mfma_f32_16x16x32_bf16 v[98:101], v[158:161], v[216:219], v[98:101]
	v_mfma_f32_16x16x32_bf16 v[126:129], v[154:157], v[196:199], v[126:129]
	v_mfma_f32_16x16x32_bf16 v[110:113], v[162:165], v[196:199], v[110:113]
	v_mfma_f32_16x16x32_bf16 v[122:125], v[154:157], v[204:207], v[122:125]
	v_mfma_f32_16x16x32_bf16 v[106:109], v[162:165], v[204:207], v[106:109]
	v_mfma_f32_16x16x32_bf16 v[118:121], v[154:157], v[212:215], v[118:121]
	v_mfma_f32_16x16x32_bf16 v[102:105], v[162:165], v[212:215], v[102:105]
	v_mfma_f32_16x16x32_bf16 v[114:117], v[154:157], v[220:223], v[114:117]
	v_mfma_f32_16x16x32_bf16 v[98:101], v[162:165], v[220:223], v[98:101]
	v_mfma_f32_16x16x32_bf16 v[70:73], v[166:169], v[192:195], v[70:73]
	v_mfma_f32_16x16x32_bf16 v[50:53], v[176:179], v[192:195], v[50:53]
	v_mfma_f32_16x16x32_bf16 v[66:69], v[166:169], v[200:203], v[66:69]
	v_mfma_f32_16x16x32_bf16 v[42:45], v[176:179], v[200:203], v[42:45]
	v_mfma_f32_16x16x32_bf16 v[58:61], v[166:169], v[208:211], v[58:61]
	v_mfma_f32_16x16x32_bf16 v[38:41], v[176:179], v[208:211], v[38:41]
	v_mfma_f32_16x16x32_bf16 v[46:49], v[166:169], v[216:219], v[46:49]
	v_mfma_f32_16x16x32_bf16 v[34:37], v[176:179], v[216:219], v[34:37]
	v_mfma_f32_16x16x32_bf16 v[70:73], v[172:175], v[196:199], v[70:73]
	v_mfma_f32_16x16x32_bf16 v[50:53], v[188:191], v[196:199], v[50:53]
	v_mfma_f32_16x16x32_bf16 v[66:69], v[172:175], v[204:207], v[66:69]
	v_mfma_f32_16x16x32_bf16 v[42:45], v[188:191], v[204:207], v[42:45]
	v_mfma_f32_16x16x32_bf16 v[58:61], v[172:175], v[212:215], v[58:61]
	v_mfma_f32_16x16x32_bf16 v[38:41], v[188:191], v[212:215], v[38:41]
	v_mfma_f32_16x16x32_bf16 v[46:49], v[172:175], v[220:223], v[46:49]
	v_mfma_f32_16x16x32_bf16 v[34:37], v[188:191], v[220:223], v[34:37]
	s_barrier
	s_setprio 0
	s_add_i32 s0, s83, s20
	s_mov_b32 m0, s0
	ds_read_b128 v[192:195], v148 offset:16384
	ds_read_b128 v[196:199], v148 offset:17408
	ds_read_b128 v[200:203], v148 offset:18432
	ds_read_b128 v[204:207], v148 offset:19456
	ds_read_b128 v[208:211], v148 offset:20480
	ds_read_b128 v[212:215], v148 offset:21504
	ds_read_b128 v[216:219], v148 offset:22528
	ds_read_b128 v[220:223], v148 offset:23552
	global_load_lds_dwordx4 v132, s[76:77]
	s_add_i32 m0, s0, 0x2000
	s_add_u32 s0, s76, 0x80000
	s_addc_u32 s1, s77, 0
	s_add_i32 s83, s84, s20
	global_load_lds_dwordx4 v136, s[76:77]
	s_mov_b32 m0, s83
	s_nop 0
	global_load_lds_dwordx4 v132, s[0:1]
	s_add_i32 m0, s83, 0x2000
	s_nop 0
	global_load_lds_dwordx4 v136, s[0:1]
	s_mov_b32 m0, s35
	s_nop 0
	global_load_lds_dwordx4 v130, s[78:79]
	s_mov_b32 m0, s37
	s_nop 0
	global_load_lds_dwordx4 v134, s[78:79]
	s_waitcnt vmcnt(8)
	s_waitcnt lgkmcnt(0)
	s_setprio 1
	s_barrier
	v_mfma_f32_16x16x32_bf16 v[94:97], v[150:153], v[192:195], v[94:97]
	v_mfma_f32_16x16x32_bf16 v[78:81], v[158:161], v[192:195], v[78:81]
	v_mfma_f32_16x16x32_bf16 v[90:93], v[150:153], v[200:203], v[90:93]
	v_mfma_f32_16x16x32_bf16 v[74:77], v[158:161], v[200:203], v[74:77]
	v_mfma_f32_16x16x32_bf16 v[86:89], v[150:153], v[208:211], v[86:89]
	v_mfma_f32_16x16x32_bf16 v[62:65], v[158:161], v[208:211], v[62:65]
	v_mfma_f32_16x16x32_bf16 v[82:85], v[150:153], v[216:219], v[82:85]
	v_mfma_f32_16x16x32_bf16 v[54:57], v[158:161], v[216:219], v[54:57]
	v_mfma_f32_16x16x32_bf16 v[94:97], v[154:157], v[196:199], v[94:97]
	v_mfma_f32_16x16x32_bf16 v[78:81], v[162:165], v[196:199], v[78:81]
	v_mfma_f32_16x16x32_bf16 v[90:93], v[154:157], v[204:207], v[90:93]
	v_mfma_f32_16x16x32_bf16 v[74:77], v[162:165], v[204:207], v[74:77]
	v_mfma_f32_16x16x32_bf16 v[86:89], v[154:157], v[212:215], v[86:89]
	v_mfma_f32_16x16x32_bf16 v[62:65], v[162:165], v[212:215], v[62:65]
	v_mfma_f32_16x16x32_bf16 v[82:85], v[154:157], v[220:223], v[82:85]
	v_mfma_f32_16x16x32_bf16 v[54:57], v[162:165], v[220:223], v[54:57]
	v_mfma_f32_16x16x32_bf16 v[30:33], v[166:169], v[192:195], v[30:33]
	v_mfma_f32_16x16x32_bf16 v[14:17], v[176:179], v[192:195], v[14:17]
	v_mfma_f32_16x16x32_bf16 v[26:29], v[166:169], v[200:203], v[26:29]
	v_mfma_f32_16x16x32_bf16 v[10:13], v[176:179], v[200:203], v[10:13]
	v_mfma_f32_16x16x32_bf16 v[22:25], v[166:169], v[208:211], v[22:25]
	v_mfma_f32_16x16x32_bf16 v[6:9], v[176:179], v[208:211], v[6:9]
	v_mfma_f32_16x16x32_bf16 v[18:21], v[166:169], v[216:219], v[18:21]
	v_mfma_f32_16x16x32_bf16 v[2:5], v[176:179], v[216:219], v[2:5]
	v_mfma_f32_16x16x32_bf16 v[30:33], v[172:175], v[196:199], v[30:33]
	v_mfma_f32_16x16x32_bf16 v[14:17], v[188:191], v[196:199], v[14:17]
	v_mfma_f32_16x16x32_bf16 v[26:29], v[172:175], v[204:207], v[26:29]
	v_mfma_f32_16x16x32_bf16 v[10:13], v[188:191], v[204:207], v[10:13]
	v_mfma_f32_16x16x32_bf16 v[22:25], v[172:175], v[212:215], v[22:25]
	v_mfma_f32_16x16x32_bf16 v[6:9], v[188:191], v[212:215], v[6:9]
	v_mfma_f32_16x16x32_bf16 v[18:21], v[172:175], v[220:223], v[18:21]
	v_mfma_f32_16x16x32_bf16 v[2:5], v[188:191], v[220:223], v[2:5]
	s_barrier
; #define PG8_STAGE(bufoff, gbase, voff) do { _Pragma("unroll") for (int _i = 0; _i < 2; ++_i) \
;         __builtin_amdgcn_global_load_lds((const unsigned*)((const char*)(gbase) + (voff)[_i]), (PG8_LAS unsigned*)(lds + (bufoff) + ldsw + _i * 8192), 16, 0, 0); } while (0)
; #define PG8_LDA(dst, b, h) do { _Pragma("unroll") for (int m = 0; m < 4; ++m) _Pragma("unroll") for (int k = 0; k < 2; ++k) dst[m][k] = *(const PG8_LAS bf16x8*)(lds + PG8_SA(b, h) + aoff + m * 2048 + k * 1024); } while (0)
; #define PG8_LDB(dst, b, h) do { _Pragma("unroll") for (int n = 0; n < 2; ++n) _Pragma("unroll") for (int k = 0; k < 2; ++k) dst[n][k] = *(const PG8_LAS bf16x8*)(lds + PG8_SB(b, h) + boff + n * 2048 + k * 1024); } while (0)
; #define PG8_WAIT_V(n) asm volatile("s_waitcnt vmcnt(" #n ")" ::: "memory")
; #define PG8_WAIT_L(n) asm volatile("s_waitcnt lgkmcnt(" #n ")" ::: "memory")
; #define PG8_BAR __builtin_amdgcn_s_barrier()
; #define PG8_SCHED __builtin_amdgcn_sched_barrier(0)
;     ...
;             PG8_LDB(B0, 1, 0); PG8_LDB(B1, 1, 1); PG8_SCHED; PG8_LDA(At, 1, 0); PG8_STAGE(PG8_SA(0, 1), a2 + hstep, voffA);
;             PG8_WAIT_V(8); PG8_WAIT_L(0); PG8_BAR; PG8_MMA(0, 0, At, B0); PG8_MMA(0, 1, At, B1); PG8_BAR; PG8_SCHED;
;             PG8_LDA(At, 1, 1); PG8_STAGE(PG8_SB(1, 0), b3, voffB); PG8_STAGE(PG8_SB(1, 1), b3 + hstep, voffB); PG8_STAGE(PG8_SA(1, 0), a3, voffA);
;             PG8_WAIT_V(8); PG8_WAIT_L(0); PG8_BAR; PG8_MMA(1, 0, At, B0); PG8_MMA(1, 1, At, B1); PG8_BAR; PG8_SCHED;
	s_setprio 0
	s_add_i32 s83, 0, 0x18000
	v_add_u32_e32 v149, s83, v146
	s_add_i32 s84, 0, 0x1c000
	ds_read_b128 v[150:153], v149
	ds_read_b128 v[154:157], v149 offset:1024
	ds_read_b128 v[158:161], v149 offset:2048
	ds_read_b128 v[162:165], v149 offset:3072
	v_add_u32_e32 v149, s84, v146
	ds_read_b128 v[166:169], v149
	ds_read_b128 v[172:175], v149 offset:1024
	ds_read_b128 v[176:179], v149 offset:2048
	ds_read_b128 v[188:191], v149 offset:3072
	s_add_u32 s0, s78, 0x80000
	s_addc_u32 s1, s79, 0
	s_mov_b32 m0, s43
	ds_read_b128 v[192:195], v148 offset:32768
	ds_read_b128 v[196:199], v148 offset:33792
	ds_read_b128 v[200:203], v148 offset:34816
	ds_read_b128 v[204:207], v148 offset:35840
	ds_read_b128 v[208:211], v148 offset:36864
	ds_read_b128 v[212:215], v148 offset:37888
	ds_read_b128 v[216:219], v148 offset:38912
	ds_read_b128 v[220:223], v148 offset:39936
	global_load_lds_dwordx4 v130, s[0:1]
	s_mov_b32 m0, s44
	s_nop 0
	global_load_lds_dwordx4 v134, s[0:1]
	s_waitcnt vmcnt(8)
	s_waitcnt lgkmcnt(0)
	s_setprio 1
	s_barrier
	v_mfma_f32_16x16x32_bf16 v[126:129], v[150:153], v[192:195], v[126:129]
	v_mfma_f32_16x16x32_bf16 v[110:113], v[158:161], v[192:195], v[110:113]
	v_mfma_f32_16x16x32_bf16 v[122:125], v[150:153], v[200:203], v[122:125]
	v_mfma_f32_16x16x32_bf16 v[106:109], v[158:161], v[200:203], v[106:109]
	v_mfma_f32_16x16x32_bf16 v[118:121], v[150:153], v[208:211], v[118:121]
	v_mfma_f32_16x16x32_bf16 v[102:105], v[158:161], v[208:211], v[102:105]
	v_mfma_f32_16x16x32_bf16 v[114:117], v[150:153], v[216:219], v[114:117]
	v_mfma_f32_16x16x32_bf16 v[98:101], v[158:161], v[216:219], v[98:101]
	v_mfma_f32_16x16x32_bf16 v[126:129], v[154:157], v[196:199], v[126:129]
	v_mfma_f32_16x16x32_bf16 v[110:113], v[162:165], v[196:199], v[110:113]
	v_mfma_f32_16x16x32_bf16 v[122:125], v[154:157], v[204:207], v[122:125]
	v_mfma_f32_16x16x32_bf16 v[106:109], v[162:165], v[204:207], v[106:109]
	v_mfma_f32_16x16x32_bf16 v[118:121], v[154:157], v[212:215], v[118:121]
	v_mfma_f32_16x16x32_bf16 v[102:105], v[162:165], v[212:215], v[102:105]
	v_mfma_f32_16x16x32_bf16 v[114:117], v[154:157], v[220:223], v[114:117]
	v_mfma_f32_16x16x32_bf16 v[98:101], v[162:165], v[220:223], v[98:101]
	v_mfma_f32_16x16x32_bf16 v[70:73], v[166:169], v[192:195], v[70:73]
	v_mfma_f32_16x16x32_bf16 v[50:53], v[176:179], v[192:195], v[50:53]
	v_mfma_f32_16x16x32_bf16 v[66:69], v[166:169], v[200:203], v[66:69]
	v_mfma_f32_16x16x32_bf16 v[42:45], v[176:179], v[200:203], v[42:45]
	v_mfma_f32_16x16x32_bf16 v[58:61], v[166:169], v[208:211], v[58:61]
	v_mfma_f32_16x16x32_bf16 v[38:41], v[176:179], v[208:211], v[38:41]
	v_mfma_f32_16x16x32_bf16 v[46:49], v[166:169], v[216:219], v[46:49]
	v_mfma_f32_16x16x32_bf16 v[34:37], v[176:179], v[216:219], v[34:37]
	v_mfma_f32_16x16x32_bf16 v[70:73], v[172:175], v[196:199], v[70:73]
	v_mfma_f32_16x16x32_bf16 v[50:53], v[188:191], v[196:199], v[50:53]
	v_mfma_f32_16x16x32_bf16 v[66:69], v[172:175], v[204:207], v[66:69]
	v_mfma_f32_16x16x32_bf16 v[42:45], v[188:191], v[204:207], v[42:45]
	v_mfma_f32_16x16x32_bf16 v[58:61], v[172:175], v[212:215], v[58:61]
	v_mfma_f32_16x16x32_bf16 v[38:41], v[188:191], v[212:215], v[38:41]
	v_mfma_f32_16x16x32_bf16 v[46:49], v[172:175], v[220:223], v[46:49]
	v_mfma_f32_16x16x32_bf16 v[34:37], v[188:191], v[220:223], v[34:37]
	s_barrier
	s_setprio 0
	s_add_i32 s0, s83, s20
	s_mov_b32 m0, s0
	ds_read_b128 v[192:195], v148 offset:49152
	ds_read_b128 v[196:199], v148 offset:50176
	ds_read_b128 v[200:203], v148 offset:51200
	ds_read_b128 v[204:207], v148 offset:52224
	ds_read_b128 v[208:211], v148 offset:53248
	ds_read_b128 v[212:215], v148 offset:54272
	ds_read_b128 v[216:219], v148 offset:55296
	ds_read_b128 v[220:223], v148 offset:56320
	s_add_u32 s100, s76, 0x80
	s_addc_u32 s101, s77, 0
	global_load_lds_dwordx4 v132, s[100:101]
	s_add_i32 m0, s0, 0x2000
	s_add_u32 s0, s76, 0x80080
	s_addc_u32 s1, s77, 0
	s_add_i32 s76, s84, s20
	global_load_lds_dwordx4 v136, s[100:101]
	s_mov_b32 m0, s76
	s_nop 0
	global_load_lds_dwordx4 v132, s[0:1]
	s_add_i32 m0, s76, 0x2000
	s_nop 0
	global_load_lds_dwordx4 v136, s[0:1]
	s_mov_b32 m0, s48
	s_nop 0
	s_add_u32 s100, s78, 0x80
	s_addc_u32 s101, s79, 0
	global_load_lds_dwordx4 v130, s[100:101]
	s_mov_b32 m0, s49
	s_nop 0
	global_load_lds_dwordx4 v134, s[100:101]
	s_waitcnt vmcnt(8)
	s_waitcnt lgkmcnt(0)
	s_setprio 1
	s_barrier
	v_mfma_f32_16x16x32_bf16 v[94:97], v[150:153], v[192:195], v[94:97]
	v_mfma_f32_16x16x32_bf16 v[78:81], v[158:161], v[192:195], v[78:81]
	v_mfma_f32_16x16x32_bf16 v[90:93], v[150:153], v[200:203], v[90:93]
	v_mfma_f32_16x16x32_bf16 v[74:77], v[158:161], v[200:203], v[74:77]
	v_mfma_f32_16x16x32_bf16 v[86:89], v[150:153], v[208:211], v[86:89]
	v_mfma_f32_16x16x32_bf16 v[62:65], v[158:161], v[208:211], v[62:65]
	v_mfma_f32_16x16x32_bf16 v[82:85], v[150:153], v[216:219], v[82:85]
	v_mfma_f32_16x16x32_bf16 v[54:57], v[158:161], v[216:219], v[54:57]
	v_mfma_f32_16x16x32_bf16 v[94:97], v[154:157], v[196:199], v[94:97]
	v_mfma_f32_16x16x32_bf16 v[78:81], v[162:165], v[196:199], v[78:81]
	v_mfma_f32_16x16x32_bf16 v[90:93], v[154:157], v[204:207], v[90:93]
	v_mfma_f32_16x16x32_bf16 v[74:77], v[162:165], v[204:207], v[74:77]
	v_mfma_f32_16x16x32_bf16 v[86:89], v[154:157], v[212:215], v[86:89]
	v_mfma_f32_16x16x32_bf16 v[62:65], v[162:165], v[212:215], v[62:65]
	v_mfma_f32_16x16x32_bf16 v[82:85], v[154:157], v[220:223], v[82:85]
	v_mfma_f32_16x16x32_bf16 v[54:57], v[162:165], v[220:223], v[54:57]
	v_mfma_f32_16x16x32_bf16 v[30:33], v[166:169], v[192:195], v[30:33]
	v_mfma_f32_16x16x32_bf16 v[14:17], v[176:179], v[192:195], v[14:17]
	v_mfma_f32_16x16x32_bf16 v[26:29], v[166:169], v[200:203], v[26:29]
	v_mfma_f32_16x16x32_bf16 v[10:13], v[176:179], v[200:203], v[10:13]
	v_mfma_f32_16x16x32_bf16 v[22:25], v[166:169], v[208:211], v[22:25]
	v_mfma_f32_16x16x32_bf16 v[6:9], v[176:179], v[208:211], v[6:9]
	v_mfma_f32_16x16x32_bf16 v[18:21], v[166:169], v[216:219], v[18:21]
	v_mfma_f32_16x16x32_bf16 v[2:5], v[176:179], v[216:219], v[2:5]
	v_mfma_f32_16x16x32_bf16 v[30:33], v[172:175], v[196:199], v[30:33]
	v_mfma_f32_16x16x32_bf16 v[14:17], v[188:191], v[196:199], v[14:17]
	v_mfma_f32_16x16x32_bf16 v[26:29], v[172:175], v[204:207], v[26:29]
	v_mfma_f32_16x16x32_bf16 v[10:13], v[188:191], v[204:207], v[10:13]
	v_mfma_f32_16x16x32_bf16 v[22:25], v[172:175], v[212:215], v[22:25]
	v_mfma_f32_16x16x32_bf16 v[6:9], v[188:191], v[212:215], v[6:9]
	v_mfma_f32_16x16x32_bf16 v[18:21], v[172:175], v[220:223], v[18:21]
	v_mfma_f32_16x16x32_bf16 v[2:5], v[188:191], v[220:223], v[2:5]
	s_barrier
	s_setprio 0
	s_add_i32 s82, s82, 2
	s_add_u32 s74, s74, 0x100
	s_addc_u32 s75, s75, 0
	s_add_u32 s80, s80, 0x100
	s_addc_u32 s81, s81, 0
	s_cmp_gt_u32 s82, 29
	s_cbranch_scc0 .LBB0_596
	s_and_b64 vcc, exec, s[62:63]
	s_cbranch_vccz .LBB0_599
	s_barrier

; #define PG8_STAGE(bufoff, gbase, voff) do { _Pragma("unroll") for (int _i = 0; _i < 2; ++_i) \
;         __builtin_amdgcn_global_load_lds((const unsigned*)((const char*)(gbase) + (voff)[_i]), (PG8_LAS unsigned*)(lds + (bufoff) + ldsw + _i * 8192), 16, 0, 0); } while (0)
; #define PG8_LDA(dst, b, h) do { _Pragma("unroll") for (int m = 0; m < 4; ++m) _Pragma("unroll") for (int k = 0; k < 2; ++k) dst[m][k] = *(const PG8_LAS bf16x8*)(lds + PG8_SA(b, h) + aoff + m * 2048 + k * 1024); } while (0)
; #define PG8_LDB(dst, b, h) do { _Pragma("unroll") for (int n = 0; n < 2; ++n) _Pragma("unroll") for (int k = 0; k < 2; ++k) dst[n][k] = *(const PG8_LAS bf16x8*)(lds + PG8_SB(b, h) + boff + n * 2048 + k * 1024); } while (0)
; #define PG8_WAIT_L(n) asm volatile("s_waitcnt lgkmcnt(" #n ")" ::: "memory")
; #define PG8_WAIT_V_SEL(sel) asm volatile("s_cmp_eq_u32 %0, 0\n\ts_cbranch_scc1 .Lw8_%=\n\ts_waitcnt vmcnt(22)\n\ts_branch .Lwd_%=\n.Lw8_%=:\n\ts_waitcnt vmcnt(8)\n.Lwd_%=:" :: "s"(sel) : "memory", "scc")
; #define PG8_BAR __builtin_amdgcn_s_barrier()
; #define PG8_SCHED __builtin_amdgcn_sched_barrier(0)
;     ...
;             PG8_LDB(B0, 0, 0); PG8_LDB(B1, 0, 1); PG8_SCHED; PG8_LDA(At, 0, 0); PG8_STAGE(PG8_SA(1, 1), a1 + hstep, voffA);
;             PG8_WAIT_V_SEL(relax);
;             PG8_WAIT_L(0); PG8_BAR; PG8_MMA(0, 0, At, B0); PG8_MMA(0, 1, At, B1); PG8_BAR; PG8_SCHED;
;             PG8_LDA(At, 0, 1); PG8_STAGE(PG8_SB(0, 0), b2, voffB); PG8_STAGE(PG8_SB(0, 1), b2 + hstep, voffB); PG8_STAGE(PG8_SA(0, 0), a2, voffA);
;             PG8_WAIT_V_SEL(relax);
;             PG8_WAIT_L(0); PG8_BAR; PG8_MMA(1, 0, At, B0); PG8_MMA(1, 1, At, B1); PG8_BAR; PG8_SCHED;
.LBB0_1170:
	s_add_u32 s0, s78, 0xfff80080
	s_addc_u32 s1, s79, -1
	s_add_i32 s85, 0, 0x10000
	s_cmp_eq_u32 s84, 28
	s_cselect_b32 s83, s40, s1
	s_cselect_b32 s82, s41, s0
	s_cselect_b32 s81, s67, s77
	s_cselect_b32 s80, s69, s75
	s_add_i32 s86, 0, 0x14000
	v_add_u32_e32 v102, s85, v224
	v_add_u32_e32 v158, s86, v224
	ds_read_b128 v[90:93], v102
	ds_read_b128 v[94:97], v102 offset:1024
	ds_read_b128 v[98:101], v102 offset:2048
	ds_read_b128 v[102:105], v102 offset:3072
	ds_read_b128 v[146:149], v158
	ds_read_b128 v[150:153], v158 offset:1024
	ds_read_b128 v[154:157], v158 offset:2048
	ds_read_b128 v[158:161], v158 offset:3072
	s_add_i32 m0, s45, 0xc000
	ds_read_b128 v[162:165], v227
	ds_read_b128 v[166:169], v227 offset:1024
	ds_read_b128 v[188:191], v227 offset:2048
	ds_read_b128 v[192:195], v227 offset:3072
	ds_read_b128 v[196:199], v227 offset:4096
	ds_read_b128 v[200:203], v227 offset:5120
	ds_read_b128 v[204:207], v227 offset:6144
	ds_read_b128 v[208:211], v227 offset:7168
	global_load_lds_dwordx4 v178, s[78:79]
	s_add_i32 m0, s45, 0xe000
	s_nop 0
	global_load_lds_dwordx4 v180, s[78:79]
	s_waitcnt vmcnt(8)
	s_waitcnt lgkmcnt(0)
	s_setprio 1
	s_barrier
	v_mfma_f32_16x16x32_bf16 v[142:145], v[90:93], v[162:165], v[142:145]
	v_mfma_f32_16x16x32_bf16 v[138:141], v[98:101], v[162:165], v[138:141]
	v_mfma_f32_16x16x32_bf16 v[126:129], v[90:93], v[188:191], v[126:129]
	v_mfma_f32_16x16x32_bf16 v[122:125], v[98:101], v[188:191], v[122:125]
	v_mfma_f32_16x16x32_bf16 v[110:113], v[90:93], v[196:199], v[110:113]
	v_mfma_f32_16x16x32_bf16 v[106:109], v[98:101], v[196:199], v[106:109]
	v_mfma_f32_16x16x32_bf16 v[78:81], v[90:93], v[204:207], v[78:81]
	v_mfma_f32_16x16x32_bf16 v[74:77], v[98:101], v[204:207], v[74:77]
	v_mfma_f32_16x16x32_bf16 v[142:145], v[94:97], v[166:169], v[142:145]
	v_mfma_f32_16x16x32_bf16 v[138:141], v[102:105], v[166:169], v[138:141]
	v_mfma_f32_16x16x32_bf16 v[126:129], v[94:97], v[192:195], v[126:129]
	v_mfma_f32_16x16x32_bf16 v[122:125], v[102:105], v[192:195], v[122:125]
	v_mfma_f32_16x16x32_bf16 v[110:113], v[94:97], v[200:203], v[110:113]
	v_mfma_f32_16x16x32_bf16 v[106:109], v[102:105], v[200:203], v[106:109]
	v_mfma_f32_16x16x32_bf16 v[78:81], v[94:97], v[208:211], v[78:81]
	v_mfma_f32_16x16x32_bf16 v[74:77], v[102:105], v[208:211], v[74:77]
	v_mfma_f32_16x16x32_bf16 v[134:137], v[146:149], v[162:165], v[134:137]
	v_mfma_f32_16x16x32_bf16 v[130:133], v[154:157], v[162:165], v[130:133]
	v_mfma_f32_16x16x32_bf16 v[118:121], v[146:149], v[188:191], v[118:121]
	v_mfma_f32_16x16x32_bf16 v[114:117], v[154:157], v[188:191], v[114:117]
	v_mfma_f32_16x16x32_bf16 v[86:89], v[146:149], v[196:199], v[86:89]
	v_mfma_f32_16x16x32_bf16 v[82:85], v[154:157], v[196:199], v[82:85]
	v_mfma_f32_16x16x32_bf16 v[70:73], v[146:149], v[204:207], v[70:73]
	v_mfma_f32_16x16x32_bf16 v[66:69], v[154:157], v[204:207], v[66:69]
	v_mfma_f32_16x16x32_bf16 v[134:137], v[150:153], v[166:169], v[134:137]
	v_mfma_f32_16x16x32_bf16 v[130:133], v[158:161], v[166:169], v[130:133]
	v_mfma_f32_16x16x32_bf16 v[118:121], v[150:153], v[192:195], v[118:121]
	v_mfma_f32_16x16x32_bf16 v[114:117], v[158:161], v[192:195], v[114:117]
	v_mfma_f32_16x16x32_bf16 v[86:89], v[150:153], v[200:203], v[86:89]
	v_mfma_f32_16x16x32_bf16 v[82:85], v[158:161], v[200:203], v[82:85]
	v_mfma_f32_16x16x32_bf16 v[70:73], v[150:153], v[208:211], v[70:73]
	v_mfma_f32_16x16x32_bf16 v[66:69], v[158:161], v[208:211], v[66:69]
	s_barrier
	s_setprio 0
	s_add_i32 s0, s85, s33
	s_mov_b32 m0, s0
	ds_read_b128 v[162:165], v227 offset:16384
	ds_read_b128 v[166:169], v227 offset:17408
	ds_read_b128 v[188:191], v227 offset:18432
	ds_read_b128 v[192:195], v227 offset:19456
	ds_read_b128 v[196:199], v227 offset:20480
	ds_read_b128 v[200:203], v227 offset:21504
	ds_read_b128 v[204:207], v227 offset:22528
	ds_read_b128 v[208:211], v227 offset:23552
	global_load_lds_dwordx4 v182, s[80:81]
	s_add_i32 m0, s0, 0x2000
	s_add_u32 s0, s80, 0x80000
	s_addc_u32 s1, s81, 0
	s_add_i32 s85, s86, s33
	global_load_lds_dwordx4 v176, s[80:81]
	s_mov_b32 m0, s85
	s_nop 0
	global_load_lds_dwordx4 v182, s[0:1]
	s_add_i32 m0, s85, 0x2000
	s_nop 0
	global_load_lds_dwordx4 v176, s[0:1]
	s_mov_b32 m0, s45
	s_nop 0
	global_load_lds_dwordx4 v172, s[82:83]
	s_mov_b32 m0, s46
	s_nop 0
	global_load_lds_dwordx4 v174, s[82:83]
	s_waitcnt vmcnt(8)
	s_waitcnt lgkmcnt(0)
	s_setprio 1
	s_barrier
	v_mfma_f32_16x16x32_bf16 v[62:65], v[90:93], v[162:165], v[62:65]
	v_mfma_f32_16x16x32_bf16 v[58:61], v[98:101], v[162:165], v[58:61]
	v_mfma_f32_16x16x32_bf16 v[46:49], v[90:93], v[188:191], v[46:49]
	v_mfma_f32_16x16x32_bf16 v[42:45], v[98:101], v[188:191], v[42:45]
	v_mfma_f32_16x16x32_bf16 v[30:33], v[90:93], v[196:199], v[30:33]
	v_mfma_f32_16x16x32_bf16 v[26:29], v[98:101], v[196:199], v[26:29]
	v_mfma_f32_16x16x32_bf16 v[14:17], v[90:93], v[204:207], v[14:17]
	v_mfma_f32_16x16x32_bf16 v[10:13], v[98:101], v[204:207], v[10:13]
	v_mfma_f32_16x16x32_bf16 v[62:65], v[94:97], v[166:169], v[62:65]
	v_mfma_f32_16x16x32_bf16 v[58:61], v[102:105], v[166:169], v[58:61]
	v_mfma_f32_16x16x32_bf16 v[46:49], v[94:97], v[192:195], v[46:49]
	v_mfma_f32_16x16x32_bf16 v[42:45], v[102:105], v[192:195], v[42:45]
	v_mfma_f32_16x16x32_bf16 v[30:33], v[94:97], v[200:203], v[30:33]
	v_mfma_f32_16x16x32_bf16 v[26:29], v[102:105], v[200:203], v[26:29]
	v_mfma_f32_16x16x32_bf16 v[14:17], v[94:97], v[208:211], v[14:17]
	v_mfma_f32_16x16x32_bf16 v[10:13], v[102:105], v[208:211], v[10:13]
	v_mfma_f32_16x16x32_bf16 v[54:57], v[146:149], v[162:165], v[54:57]
	v_mfma_f32_16x16x32_bf16 v[50:53], v[154:157], v[162:165], v[50:53]
	v_mfma_f32_16x16x32_bf16 v[38:41], v[146:149], v[188:191], v[38:41]
	v_mfma_f32_16x16x32_bf16 v[34:37], v[154:157], v[188:191], v[34:37]
	v_mfma_f32_16x16x32_bf16 v[22:25], v[146:149], v[196:199], v[22:25]
	v_mfma_f32_16x16x32_bf16 v[18:21], v[154:157], v[196:199], v[18:21]
	v_mfma_f32_16x16x32_bf16 v[6:9], v[146:149], v[204:207], v[6:9]
	v_mfma_f32_16x16x32_bf16 v[2:5], v[154:157], v[204:207], v[2:5]
	v_mfma_f32_16x16x32_bf16 v[54:57], v[150:153], v[166:169], v[54:57]
	v_mfma_f32_16x16x32_bf16 v[50:53], v[158:161], v[166:169], v[50:53]
	v_mfma_f32_16x16x32_bf16 v[38:41], v[150:153], v[192:195], v[38:41]
	v_mfma_f32_16x16x32_bf16 v[34:37], v[158:161], v[192:195], v[34:37]
	v_mfma_f32_16x16x32_bf16 v[22:25], v[150:153], v[200:203], v[22:25]
	v_mfma_f32_16x16x32_bf16 v[18:21], v[158:161], v[200:203], v[18:21]
	v_mfma_f32_16x16x32_bf16 v[6:9], v[150:153], v[208:211], v[6:9]
	v_mfma_f32_16x16x32_bf16 v[2:5], v[158:161], v[208:211], v[2:5]
	s_barrier
; #define PG8_STAGE(bufoff, gbase, voff) do { _Pragma("unroll") for (int _i = 0; _i < 2; ++_i) \
;         __builtin_amdgcn_global_load_lds((const unsigned*)((const char*)(gbase) + (voff)[_i]), (PG8_LAS unsigned*)(lds + (bufoff) + ldsw + _i * 8192), 16, 0, 0); } while (0)
; #define PG8_LDA(dst, b, h) do { _Pragma("unroll") for (int m = 0; m < 4; ++m) _Pragma("unroll") for (int k = 0; k < 2; ++k) dst[m][k] = *(const PG8_LAS bf16x8*)(lds + PG8_SA(b, h) + aoff + m * 2048 + k * 1024); } while (0)
; #define PG8_LDB(dst, b, h) do { _Pragma("unroll") for (int n = 0; n < 2; ++n) _Pragma("unroll") for (int k = 0; k < 2; ++k) dst[n][k] = *(const PG8_LAS bf16x8*)(lds + PG8_SB(b, h) + boff + n * 2048 + k * 1024); } while (0)
; #define PG8_WAIT_V(n) asm volatile("s_waitcnt vmcnt(" #n ")" ::: "memory")
; #define PG8_WAIT_L(n) asm volatile("s_waitcnt lgkmcnt(" #n ")" ::: "memory")
; #define PG8_BAR __builtin_amdgcn_s_barrier()
; #define PG8_SCHED __builtin_amdgcn_sched_barrier(0)
;     ...
;             PG8_LDB(B0, 1, 0); PG8_LDB(B1, 1, 1); PG8_SCHED; PG8_LDA(At, 1, 0); PG8_STAGE(PG8_SA(0, 1), a2 + hstep, voffA);
;             PG8_WAIT_V(8); PG8_WAIT_L(0); PG8_BAR; PG8_MMA(0, 0, At, B0); PG8_MMA(0, 1, At, B1); PG8_BAR; PG8_SCHED;
;             PG8_LDA(At, 1, 1); PG8_STAGE(PG8_SB(1, 0), b3, voffB); PG8_STAGE(PG8_SB(1, 1), b3 + hstep, voffB); PG8_STAGE(PG8_SA(1, 0), a3, voffA);
;             PG8_WAIT_V(8); PG8_WAIT_L(0); PG8_BAR; PG8_MMA(1, 0, At, B0); PG8_MMA(1, 1, At, B1); PG8_BAR; PG8_SCHED;
	s_setprio 0
	s_add_i32 s85, 0, 0x18000
	s_add_i32 s86, 0, 0x1c000
	v_add_u32_e32 v102, s85, v224
	v_add_u32_e32 v158, s86, v224
	ds_read_b128 v[90:93], v102
	ds_read_b128 v[94:97], v102 offset:1024
	ds_read_b128 v[98:101], v102 offset:2048
	ds_read_b128 v[102:105], v102 offset:3072
	ds_read_b128 v[146:149], v158
	ds_read_b128 v[150:153], v158 offset:1024
	ds_read_b128 v[154:157], v158 offset:2048
	ds_read_b128 v[158:161], v158 offset:3072
	s_add_u32 s0, s82, 0x80000
	s_addc_u32 s1, s83, 0
	s_mov_b32 m0, s47
	ds_read_b128 v[162:165], v227 offset:32768
	ds_read_b128 v[166:169], v227 offset:33792
	ds_read_b128 v[188:191], v227 offset:34816
	ds_read_b128 v[192:195], v227 offset:35840
	ds_read_b128 v[196:199], v227 offset:36864
	ds_read_b128 v[200:203], v227 offset:37888
	ds_read_b128 v[204:207], v227 offset:38912
	ds_read_b128 v[208:211], v227 offset:39936
	global_load_lds_dwordx4 v172, s[0:1]
	s_mov_b32 m0, s48
	s_nop 0
	global_load_lds_dwordx4 v174, s[0:1]
	s_waitcnt vmcnt(8)
	s_waitcnt lgkmcnt(0)
	s_setprio 1
	s_barrier
	v_mfma_f32_16x16x32_bf16 v[142:145], v[90:93], v[162:165], v[142:145]
	v_mfma_f32_16x16x32_bf16 v[138:141], v[98:101], v[162:165], v[138:141]
	v_mfma_f32_16x16x32_bf16 v[126:129], v[90:93], v[188:191], v[126:129]
	v_mfma_f32_16x16x32_bf16 v[122:125], v[98:101], v[188:191], v[122:125]
	v_mfma_f32_16x16x32_bf16 v[110:113], v[90:93], v[196:199], v[110:113]
	v_mfma_f32_16x16x32_bf16 v[106:109], v[98:101], v[196:199], v[106:109]
	v_mfma_f32_16x16x32_bf16 v[78:81], v[90:93], v[204:207], v[78:81]
	v_mfma_f32_16x16x32_bf16 v[74:77], v[98:101], v[204:207], v[74:77]
	v_mfma_f32_16x16x32_bf16 v[142:145], v[94:97], v[166:169], v[142:145]
	v_mfma_f32_16x16x32_bf16 v[138:141], v[102:105], v[166:169], v[138:141]
	v_mfma_f32_16x16x32_bf16 v[126:129], v[94:97], v[192:195], v[126:129]
	v_mfma_f32_16x16x32_bf16 v[122:125], v[102:105], v[192:195], v[122:125]
	v_mfma_f32_16x16x32_bf16 v[110:113], v[94:97], v[200:203], v[110:113]
	v_mfma_f32_16x16x32_bf16 v[106:109], v[102:105], v[200:203], v[106:109]
	v_mfma_f32_16x16x32_bf16 v[78:81], v[94:97], v[208:211], v[78:81]
	v_mfma_f32_16x16x32_bf16 v[74:77], v[102:105], v[208:211], v[74:77]
	v_mfma_f32_16x16x32_bf16 v[134:137], v[146:149], v[162:165], v[134:137]
	v_mfma_f32_16x16x32_bf16 v[130:133], v[154:157], v[162:165], v[130:133]
	v_mfma_f32_16x16x32_bf16 v[118:121], v[146:149], v[188:191], v[118:121]
	v_mfma_f32_16x16x32_bf16 v[114:117], v[154:157], v[188:191], v[114:117]
	v_mfma_f32_16x16x32_bf16 v[86:89], v[146:149], v[196:199], v[86:89]
	v_mfma_f32_16x16x32_bf16 v[82:85], v[154:157], v[196:199], v[82:85]
	v_mfma_f32_16x16x32_bf16 v[70:73], v[146:149], v[204:207], v[70:73]
	v_mfma_f32_16x16x32_bf16 v[66:69], v[154:157], v[204:207], v[66:69]
	v_mfma_f32_16x16x32_bf16 v[134:137], v[150:153], v[166:169], v[134:137]
	v_mfma_f32_16x16x32_bf16 v[130:133], v[158:161], v[166:169], v[130:133]
	v_mfma_f32_16x16x32_bf16 v[118:121], v[150:153], v[192:195], v[118:121]
	v_mfma_f32_16x16x32_bf16 v[114:117], v[158:161], v[192:195], v[114:117]
	v_mfma_f32_16x16x32_bf16 v[86:89], v[150:153], v[200:203], v[86:89]
	v_mfma_f32_16x16x32_bf16 v[82:85], v[158:161], v[200:203], v[82:85]
	v_mfma_f32_16x16x32_bf16 v[70:73], v[150:153], v[208:211], v[70:73]
	v_mfma_f32_16x16x32_bf16 v[66:69], v[158:161], v[208:211], v[66:69]
	s_barrier
	s_setprio 0
	s_add_i32 s0, s85, s33
	s_mov_b32 m0, s0
	ds_read_b128 v[162:165], v227 offset:49152
	ds_read_b128 v[166:169], v227 offset:50176
	ds_read_b128 v[188:191], v227 offset:51200
	ds_read_b128 v[192:195], v227 offset:52224
	ds_read_b128 v[196:199], v227 offset:53248
	ds_read_b128 v[200:203], v227 offset:54272
	ds_read_b128 v[204:207], v227 offset:55296
	ds_read_b128 v[208:211], v227 offset:56320
	s_add_u32 s100, s80, 0x80
	s_addc_u32 s101, s81, 0
	global_load_lds_dwordx4 v182, s[100:101]
	s_add_i32 m0, s0, 0x2000
	s_add_u32 s0, s80, 0x80080
	s_addc_u32 s1, s81, 0
	s_add_i32 s80, s86, s33
	global_load_lds_dwordx4 v176, s[100:101]
	s_mov_b32 m0, s80
	s_nop 0
	global_load_lds_dwordx4 v182, s[0:1]
	s_add_i32 m0, s80, 0x2000
	s_nop 0
	global_load_lds_dwordx4 v176, s[0:1]
	s_mov_b32 m0, s50
	s_nop 0
	s_add_u32 s100, s82, 0x80
	s_addc_u32 s101, s83, 0
	global_load_lds_dwordx4 v172, s[100:101]
	s_mov_b32 m0, s51
	s_nop 0
	global_load_lds_dwordx4 v174, s[100:101]
	s_waitcnt vmcnt(8)
	s_waitcnt lgkmcnt(0)
	s_setprio 1
	s_barrier
	v_mfma_f32_16x16x32_bf16 v[62:65], v[90:93], v[162:165], v[62:65]
	v_mfma_f32_16x16x32_bf16 v[58:61], v[98:101], v[162:165], v[58:61]
	v_mfma_f32_16x16x32_bf16 v[46:49], v[90:93], v[188:191], v[46:49]
	v_mfma_f32_16x16x32_bf16 v[42:45], v[98:101], v[188:191], v[42:45]
	v_mfma_f32_16x16x32_bf16 v[30:33], v[90:93], v[196:199], v[30:33]
	v_mfma_f32_16x16x32_bf16 v[26:29], v[98:101], v[196:199], v[26:29]
	v_mfma_f32_16x16x32_bf16 v[14:17], v[90:93], v[204:207], v[14:17]
	v_mfma_f32_16x16x32_bf16 v[10:13], v[98:101], v[204:207], v[10:13]
	v_mfma_f32_16x16x32_bf16 v[62:65], v[94:97], v[166:169], v[62:65]
	v_mfma_f32_16x16x32_bf16 v[58:61], v[102:105], v[166:169], v[58:61]
	v_mfma_f32_16x16x32_bf16 v[46:49], v[94:97], v[192:195], v[46:49]
	v_mfma_f32_16x16x32_bf16 v[42:45], v[102:105], v[192:195], v[42:45]
	v_mfma_f32_16x16x32_bf16 v[30:33], v[94:97], v[200:203], v[30:33]
	v_mfma_f32_16x16x32_bf16 v[26:29], v[102:105], v[200:203], v[26:29]
	v_mfma_f32_16x16x32_bf16 v[14:17], v[94:97], v[208:211], v[14:17]
	v_mfma_f32_16x16x32_bf16 v[10:13], v[102:105], v[208:211], v[10:13]
	v_mfma_f32_16x16x32_bf16 v[54:57], v[146:149], v[162:165], v[54:57]
	v_mfma_f32_16x16x32_bf16 v[50:53], v[154:157], v[162:165], v[50:53]
	v_mfma_f32_16x16x32_bf16 v[38:41], v[146:149], v[188:191], v[38:41]
	v_mfma_f32_16x16x32_bf16 v[34:37], v[154:157], v[188:191], v[34:37]
	v_mfma_f32_16x16x32_bf16 v[22:25], v[146:149], v[196:199], v[22:25]
	v_mfma_f32_16x16x32_bf16 v[18:21], v[154:157], v[196:199], v[18:21]
	v_mfma_f32_16x16x32_bf16 v[6:9], v[146:149], v[204:207], v[6:9]
	v_mfma_f32_16x16x32_bf16 v[2:5], v[154:157], v[204:207], v[2:5]
	v_mfma_f32_16x16x32_bf16 v[54:57], v[150:153], v[166:169], v[54:57]
	v_mfma_f32_16x16x32_bf16 v[50:53], v[158:161], v[166:169], v[50:53]
	v_mfma_f32_16x16x32_bf16 v[38:41], v[150:153], v[192:195], v[38:41]
	v_mfma_f32_16x16x32_bf16 v[34:37], v[158:161], v[192:195], v[34:37]
	v_mfma_f32_16x16x32_bf16 v[22:25], v[150:153], v[200:203], v[22:25]
	v_mfma_f32_16x16x32_bf16 v[18:21], v[158:161], v[200:203], v[18:21]
	v_mfma_f32_16x16x32_bf16 v[6:9], v[150:153], v[208:211], v[6:9]
	v_mfma_f32_16x16x32_bf16 v[2:5], v[158:161], v[208:211], v[2:5]
	s_barrier
	s_setprio 0
	s_add_i32 s84, s84, 2
	s_add_u32 s78, s78, 0x100
	s_addc_u32 s79, s79, 0
	s_add_u32 s75, s75, 0x100
	s_addc_u32 s77, s77, 0
	s_cmp_gt_u32 s84, 29
	s_cbranch_scc0 .LBB0_1170
	s_and_b64 vcc, exec, s[64:65]
	s_cbranch_vccz .LBB0_1173
	s_barrier

; #define PG8_STAGE(bufoff, gbase, voff) do { _Pragma("unroll") for (int _i = 0; _i < 2; ++_i) \
;         __builtin_amdgcn_global_load_lds((const unsigned*)((const char*)(gbase) + (voff)[_i]), (PG8_LAS unsigned*)(lds + (bufoff) + ldsw + _i * 8192), 16, 0, 0); } while (0)
; #define PG8_LDA(dst, b, h) do { _Pragma("unroll") for (int m = 0; m < 4; ++m) _Pragma("unroll") for (int k = 0; k < 2; ++k) dst[m][k] = *(const PG8_LAS bf16x8*)(lds + PG8_SA(b, h) + aoff + m * 2048 + k * 1024); } while (0)
; #define PG8_LDB(dst, b, h) do { _Pragma("unroll") for (int n = 0; n < 2; ++n) _Pragma("unroll") for (int k = 0; k < 2; ++k) dst[n][k] = *(const PG8_LAS bf16x8*)(lds + PG8_SB(b, h) + boff + n * 2048 + k * 1024); } while (0)
; #define PG8_WAIT_L(n) asm volatile("s_waitcnt lgkmcnt(" #n ")" ::: "memory")
; #define PG8_WAIT_V_SEL(sel) asm volatile("s_cmp_eq_u32 %0, 0\n\ts_cbranch_scc1 .Lw8_%=\n\ts_waitcnt vmcnt(22)\n\ts_branch .Lwd_%=\n.Lw8_%=:\n\ts_waitcnt vmcnt(8)\n.Lwd_%=:" :: "s"(sel) : "memory", "scc")
; #define PG8_BAR __builtin_amdgcn_s_barrier()
; #define PG8_SCHED __builtin_amdgcn_sched_barrier(0)
;     ...
;             PG8_LDB(B0, 0, 0); PG8_LDB(B1, 0, 1); PG8_SCHED; PG8_LDA(At, 0, 0); PG8_STAGE(PG8_SA(1, 1), a1 + hstep, voffA);
;             PG8_WAIT_V_SEL(relax);
;             PG8_WAIT_L(0); PG8_BAR; PG8_MMA(0, 0, At, B0); PG8_MMA(0, 1, At, B1); PG8_BAR; PG8_SCHED;
;             PG8_LDA(At, 0, 1); PG8_STAGE(PG8_SB(0, 0), b2, voffB); PG8_STAGE(PG8_SB(0, 1), b2 + hstep, voffB); PG8_STAGE(PG8_SA(0, 0), a2, voffA);
;             PG8_WAIT_V_SEL(relax);
;             PG8_WAIT_L(0); PG8_BAR; PG8_MMA(1, 0, At, B0); PG8_MMA(1, 1, At, B1); PG8_BAR; PG8_SCHED;
.LBB0_1327:
	s_add_u32 s96, s12, 0x100
	s_addc_u32 s97, s13, 0
	s_add_i32 s51, 0, 0x10000
	s_cmp_eq_u32 s0, 28
	s_cselect_b32 s41, s59, s97
	s_cselect_b32 s40, s64, s96
	s_cselect_b32 vcc_hi, s65, s67
	s_cselect_b32 vcc_lo, s87, s66
	s_add_i32 s19, 0, 0x14000
	v_add_u32_e32 v142, s51, v203
	v_add_u32_e32 v158, s19, v203
	ds_read_b128 v[66:69], v142
	ds_read_b128 v[70:73], v142 offset:1024
	ds_read_b128 v[82:85], v142 offset:2048
	ds_read_b128 v[142:145], v142 offset:3072
	ds_read_b128 v[146:149], v158
	ds_read_b128 v[150:153], v158 offset:1024
	ds_read_b128 v[154:157], v158 offset:2048
	ds_read_b128 v[158:161], v158 offset:3072
	s_add_i32 m0, s95, 0xc000
	ds_read_b128 v[162:165], v219
	ds_read_b128 v[166:169], v219 offset:1024
	ds_read_b128 v[170:173], v219 offset:2048
	ds_read_b128 v[174:177], v219 offset:3072
	ds_read_b128 v[178:181], v219 offset:4096
	ds_read_b128 v[184:187], v219 offset:5120
	ds_read_b128 v[220:223], v219 offset:6144
	ds_read_b128 v[224:227], v219 offset:7168
	global_load_lds_dwordx4 v196, s[12:13]
	s_add_i32 m0, s95, 0xe000
	s_nop 0
	global_load_lds_dwordx4 v198, s[12:13]
	s_waitcnt vmcnt(8)
	s_waitcnt lgkmcnt(0)
	s_setprio 1
	s_barrier
	v_mfma_f32_16x16x32_bf16 v[114:117], v[66:69], v[162:165], v[114:117]
	v_mfma_f32_16x16x32_bf16 v[106:109], v[82:85], v[162:165], v[106:109]
	v_mfma_f32_16x16x32_bf16 v[110:113], v[66:69], v[170:173], v[110:113]
	v_mfma_f32_16x16x32_bf16 v[102:105], v[82:85], v[170:173], v[102:105]
	v_mfma_f32_16x16x32_bf16 v[78:81], v[66:69], v[178:181], v[78:81]
	v_mfma_f32_16x16x32_bf16 v[138:141], v[82:85], v[178:181], v[138:141]
	v_mfma_f32_16x16x32_bf16 v[74:77], v[66:69], v[220:223], v[74:77]
	v_mfma_f32_16x16x32_bf16 v[134:137], v[82:85], v[220:223], v[134:137]
	v_mfma_f32_16x16x32_bf16 v[114:117], v[70:73], v[166:169], v[114:117]
	v_mfma_f32_16x16x32_bf16 v[106:109], v[142:145], v[166:169], v[106:109]
	v_mfma_f32_16x16x32_bf16 v[110:113], v[70:73], v[174:177], v[110:113]
	v_mfma_f32_16x16x32_bf16 v[102:105], v[142:145], v[174:177], v[102:105]
	v_mfma_f32_16x16x32_bf16 v[78:81], v[70:73], v[184:187], v[78:81]
	v_mfma_f32_16x16x32_bf16 v[138:141], v[142:145], v[184:187], v[138:141]
	v_mfma_f32_16x16x32_bf16 v[74:77], v[70:73], v[224:227], v[74:77]
	v_mfma_f32_16x16x32_bf16 v[134:137], v[142:145], v[224:227], v[134:137]
	v_mfma_f32_16x16x32_bf16 v[98:101], v[146:149], v[162:165], v[98:101]
	v_mfma_f32_16x16x32_bf16 v[90:93], v[154:157], v[162:165], v[90:93]
	v_mfma_f32_16x16x32_bf16 v[94:97], v[146:149], v[170:173], v[94:97]
	v_mfma_f32_16x16x32_bf16 v[86:89], v[154:157], v[170:173], v[86:89]
	v_mfma_f32_16x16x32_bf16 v[130:133], v[146:149], v[178:181], v[130:133]
	v_mfma_f32_16x16x32_bf16 v[122:125], v[154:157], v[178:181], v[122:125]
	v_mfma_f32_16x16x32_bf16 v[126:129], v[146:149], v[220:223], v[126:129]
	v_mfma_f32_16x16x32_bf16 v[118:121], v[154:157], v[220:223], v[118:121]
	v_mfma_f32_16x16x32_bf16 v[98:101], v[150:153], v[166:169], v[98:101]
	v_mfma_f32_16x16x32_bf16 v[90:93], v[158:161], v[166:169], v[90:93]
	v_mfma_f32_16x16x32_bf16 v[94:97], v[150:153], v[174:177], v[94:97]
	v_mfma_f32_16x16x32_bf16 v[86:89], v[158:161], v[174:177], v[86:89]
	v_mfma_f32_16x16x32_bf16 v[130:133], v[150:153], v[184:187], v[130:133]
	v_mfma_f32_16x16x32_bf16 v[122:125], v[158:161], v[184:187], v[122:125]
	v_mfma_f32_16x16x32_bf16 v[126:129], v[150:153], v[224:227], v[126:129]
	v_mfma_f32_16x16x32_bf16 v[118:121], v[158:161], v[224:227], v[118:121]
	s_barrier
	s_setprio 0
	s_add_i32 s12, s51, s37
	s_mov_b32 m0, s12
	ds_read_b128 v[162:165], v219 offset:16384
	ds_read_b128 v[166:169], v219 offset:17408
	ds_read_b128 v[170:173], v219 offset:18432
	ds_read_b128 v[174:177], v219 offset:19456
	ds_read_b128 v[178:181], v219 offset:20480
	ds_read_b128 v[184:187], v219 offset:21504
	ds_read_b128 v[220:223], v219 offset:22528
	ds_read_b128 v[224:227], v219 offset:23552
	global_load_lds_dwordx4 v182, vcc
	s_add_i32 m0, s12, 0x2000
	s_add_u32 s12, vcc_lo, 0x80000
	s_addc_u32 s13, vcc_hi, 0
	s_add_i32 s19, s19, s37
	global_load_lds_dwordx4 v192, vcc
	s_mov_b32 m0, s19
	s_nop 0
	global_load_lds_dwordx4 v182, s[12:13]
	s_add_i32 m0, s19, 0x2000
	s_nop 0
	global_load_lds_dwordx4 v192, s[12:13]
	s_mov_b32 m0, s95
	s_nop 0
	global_load_lds_dwordx4 v188, s[40:41]
	s_mov_b32 m0, s20
	s_nop 0
	global_load_lds_dwordx4 v190, s[40:41]
	s_waitcnt vmcnt(8)
	s_waitcnt lgkmcnt(0)
	s_setprio 1
	s_barrier
	v_mfma_f32_16x16x32_bf16 v[30:33], v[66:69], v[162:165], v[30:33]
	v_mfma_f32_16x16x32_bf16 v[22:25], v[82:85], v[162:165], v[22:25]
	v_mfma_f32_16x16x32_bf16 v[26:29], v[66:69], v[170:173], v[26:29]
	v_mfma_f32_16x16x32_bf16 v[18:21], v[82:85], v[170:173], v[18:21]
	v_mfma_f32_16x16x32_bf16 v[62:65], v[66:69], v[178:181], v[62:65]
	v_mfma_f32_16x16x32_bf16 v[54:57], v[82:85], v[178:181], v[54:57]
	v_mfma_f32_16x16x32_bf16 v[58:61], v[66:69], v[220:223], v[58:61]
	v_mfma_f32_16x16x32_bf16 v[50:53], v[82:85], v[220:223], v[50:53]
	v_mfma_f32_16x16x32_bf16 v[30:33], v[70:73], v[166:169], v[30:33]
	v_mfma_f32_16x16x32_bf16 v[22:25], v[142:145], v[166:169], v[22:25]
	v_mfma_f32_16x16x32_bf16 v[26:29], v[70:73], v[174:177], v[26:29]
	v_mfma_f32_16x16x32_bf16 v[18:21], v[142:145], v[174:177], v[18:21]
	v_mfma_f32_16x16x32_bf16 v[62:65], v[70:73], v[184:187], v[62:65]
	v_mfma_f32_16x16x32_bf16 v[54:57], v[142:145], v[184:187], v[54:57]
	v_mfma_f32_16x16x32_bf16 v[58:61], v[70:73], v[224:227], v[58:61]
	v_mfma_f32_16x16x32_bf16 v[50:53], v[142:145], v[224:227], v[50:53]
	v_mfma_f32_16x16x32_bf16 v[14:17], v[146:149], v[162:165], v[14:17]
	v_mfma_f32_16x16x32_bf16 v[6:9], v[154:157], v[162:165], v[6:9]
	v_mfma_f32_16x16x32_bf16 v[10:13], v[146:149], v[170:173], v[10:13]
	v_mfma_f32_16x16x32_bf16 v[2:5], v[154:157], v[170:173], v[2:5]
	v_mfma_f32_16x16x32_bf16 v[46:49], v[146:149], v[178:181], v[46:49]
	v_mfma_f32_16x16x32_bf16 v[34:37], v[154:157], v[178:181], v[34:37]
	v_mfma_f32_16x16x32_bf16 v[38:41], v[146:149], v[220:223], v[38:41]
	v_mfma_f32_16x16x32_bf16 v[42:45], v[154:157], v[220:223], v[42:45]
	v_mfma_f32_16x16x32_bf16 v[14:17], v[150:153], v[166:169], v[14:17]
	v_mfma_f32_16x16x32_bf16 v[6:9], v[158:161], v[166:169], v[6:9]
	v_mfma_f32_16x16x32_bf16 v[10:13], v[150:153], v[174:177], v[10:13]
	v_mfma_f32_16x16x32_bf16 v[2:5], v[158:161], v[174:177], v[2:5]
	v_mfma_f32_16x16x32_bf16 v[46:49], v[150:153], v[184:187], v[46:49]
	v_mfma_f32_16x16x32_bf16 v[34:37], v[158:161], v[184:187], v[34:37]
	v_mfma_f32_16x16x32_bf16 v[38:41], v[150:153], v[224:227], v[38:41]
	v_mfma_f32_16x16x32_bf16 v[42:45], v[158:161], v[224:227], v[42:45]
	s_barrier
; #define PG8_STAGE(bufoff, gbase, voff) do { _Pragma("unroll") for (int _i = 0; _i < 2; ++_i) \
;         __builtin_amdgcn_global_load_lds((const unsigned*)((const char*)(gbase) + (voff)[_i]), (PG8_LAS unsigned*)(lds + (bufoff) + ldsw + _i * 8192), 16, 0, 0); } while (0)
; #define PG8_LDA(dst, b, h) do { _Pragma("unroll") for (int m = 0; m < 4; ++m) _Pragma("unroll") for (int k = 0; k < 2; ++k) dst[m][k] = *(const PG8_LAS bf16x8*)(lds + PG8_SA(b, h) + aoff + m * 2048 + k * 1024); } while (0)
; #define PG8_LDB(dst, b, h) do { _Pragma("unroll") for (int n = 0; n < 2; ++n) _Pragma("unroll") for (int k = 0; k < 2; ++k) dst[n][k] = *(const PG8_LAS bf16x8*)(lds + PG8_SB(b, h) + boff + n * 2048 + k * 1024); } while (0)
; #define PG8_WAIT_V(n) asm volatile("s_waitcnt vmcnt(" #n ")" ::: "memory")
; #define PG8_WAIT_L(n) asm volatile("s_waitcnt lgkmcnt(" #n ")" ::: "memory")
; #define PG8_BAR __builtin_amdgcn_s_barrier()
; #define PG8_SCHED __builtin_amdgcn_sched_barrier(0)
;     ...
;             PG8_LDB(B0, 1, 0); PG8_LDB(B1, 1, 1); PG8_SCHED; PG8_LDA(At, 1, 0); PG8_STAGE(PG8_SA(0, 1), a2 + hstep, voffA);
;             PG8_WAIT_V(8); PG8_WAIT_L(0); PG8_BAR; PG8_MMA(0, 0, At, B0); PG8_MMA(0, 1, At, B1); PG8_BAR; PG8_SCHED;
;             PG8_LDA(At, 1, 1); PG8_STAGE(PG8_SB(1, 0), b3, voffB); PG8_STAGE(PG8_SB(1, 1), b3 + hstep, voffB); PG8_STAGE(PG8_SA(1, 0), a3, voffA);
;             PG8_WAIT_V(8); PG8_WAIT_L(0); PG8_BAR; PG8_MMA(1, 0, At, B0); PG8_MMA(1, 1, At, B1); PG8_BAR; PG8_SCHED;
	s_setprio 0
	s_add_i32 s19, 0, 0x18000
	s_add_i32 s51, 0, 0x1c000
	v_add_u32_e32 v142, s19, v203
	v_add_u32_e32 v158, s51, v203
	ds_read_b128 v[66:69], v142
	ds_read_b128 v[70:73], v142 offset:1024
	ds_read_b128 v[82:85], v142 offset:2048
	ds_read_b128 v[142:145], v142 offset:3072
	ds_read_b128 v[146:149], v158
	ds_read_b128 v[150:153], v158 offset:1024
	ds_read_b128 v[154:157], v158 offset:2048
	ds_read_b128 v[158:161], v158 offset:3072
	s_add_u32 s12, s40, 0x80000
	s_addc_u32 s13, s41, 0
	s_mov_b32 m0, s44
	ds_read_b128 v[162:165], v219 offset:32768
	ds_read_b128 v[166:169], v219 offset:33792
	ds_read_b128 v[170:173], v219 offset:34816
	ds_read_b128 v[174:177], v219 offset:35840
	ds_read_b128 v[178:181], v219 offset:36864
	ds_read_b128 v[184:187], v219 offset:37888
	ds_read_b128 v[220:223], v219 offset:38912
	ds_read_b128 v[224:227], v219 offset:39936
	global_load_lds_dwordx4 v188, s[12:13]
	s_mov_b32 m0, s46
	s_nop 0
	global_load_lds_dwordx4 v190, s[12:13]
	s_waitcnt vmcnt(8)
	s_waitcnt lgkmcnt(0)
	s_setprio 1
	s_barrier
	v_mfma_f32_16x16x32_bf16 v[114:117], v[66:69], v[162:165], v[114:117]
	v_mfma_f32_16x16x32_bf16 v[106:109], v[82:85], v[162:165], v[106:109]
	v_mfma_f32_16x16x32_bf16 v[110:113], v[66:69], v[170:173], v[110:113]
	v_mfma_f32_16x16x32_bf16 v[102:105], v[82:85], v[170:173], v[102:105]
	v_mfma_f32_16x16x32_bf16 v[78:81], v[66:69], v[178:181], v[78:81]
	v_mfma_f32_16x16x32_bf16 v[138:141], v[82:85], v[178:181], v[138:141]
	v_mfma_f32_16x16x32_bf16 v[74:77], v[66:69], v[220:223], v[74:77]
	v_mfma_f32_16x16x32_bf16 v[134:137], v[82:85], v[220:223], v[134:137]
	v_mfma_f32_16x16x32_bf16 v[114:117], v[70:73], v[166:169], v[114:117]
	v_mfma_f32_16x16x32_bf16 v[106:109], v[142:145], v[166:169], v[106:109]
	v_mfma_f32_16x16x32_bf16 v[110:113], v[70:73], v[174:177], v[110:113]
	v_mfma_f32_16x16x32_bf16 v[102:105], v[142:145], v[174:177], v[102:105]
	v_mfma_f32_16x16x32_bf16 v[78:81], v[70:73], v[184:187], v[78:81]
	v_mfma_f32_16x16x32_bf16 v[138:141], v[142:145], v[184:187], v[138:141]
	v_mfma_f32_16x16x32_bf16 v[74:77], v[70:73], v[224:227], v[74:77]
	v_mfma_f32_16x16x32_bf16 v[134:137], v[142:145], v[224:227], v[134:137]
	v_mfma_f32_16x16x32_bf16 v[98:101], v[146:149], v[162:165], v[98:101]
	v_mfma_f32_16x16x32_bf16 v[90:93], v[154:157], v[162:165], v[90:93]
	v_mfma_f32_16x16x32_bf16 v[94:97], v[146:149], v[170:173], v[94:97]
	v_mfma_f32_16x16x32_bf16 v[86:89], v[154:157], v[170:173], v[86:89]
	v_mfma_f32_16x16x32_bf16 v[130:133], v[146:149], v[178:181], v[130:133]
	v_mfma_f32_16x16x32_bf16 v[122:125], v[154:157], v[178:181], v[122:125]
	v_mfma_f32_16x16x32_bf16 v[126:129], v[146:149], v[220:223], v[126:129]
	v_mfma_f32_16x16x32_bf16 v[118:121], v[154:157], v[220:223], v[118:121]
	v_mfma_f32_16x16x32_bf16 v[98:101], v[150:153], v[166:169], v[98:101]
	v_mfma_f32_16x16x32_bf16 v[90:93], v[158:161], v[166:169], v[90:93]
	v_mfma_f32_16x16x32_bf16 v[94:97], v[150:153], v[174:177], v[94:97]
	v_mfma_f32_16x16x32_bf16 v[86:89], v[158:161], v[174:177], v[86:89]
	v_mfma_f32_16x16x32_bf16 v[130:133], v[150:153], v[184:187], v[130:133]
	v_mfma_f32_16x16x32_bf16 v[122:125], v[158:161], v[184:187], v[122:125]
	v_mfma_f32_16x16x32_bf16 v[126:129], v[150:153], v[224:227], v[126:129]
	v_mfma_f32_16x16x32_bf16 v[118:121], v[158:161], v[224:227], v[118:121]
	s_barrier
	s_setprio 0
	s_add_i32 s12, s19, s37
	s_mov_b32 m0, s12
	ds_read_b128 v[162:165], v219 offset:49152
	ds_read_b128 v[166:169], v219 offset:50176
	ds_read_b128 v[170:173], v219 offset:51200
	ds_read_b128 v[174:177], v219 offset:52224
	ds_read_b128 v[178:181], v219 offset:53248
	ds_read_b128 v[184:187], v219 offset:54272
	ds_read_b128 v[220:223], v219 offset:55296
	ds_read_b128 v[224:227], v219 offset:56320
	s_add_u32 s100, vcc_lo, 0x80
	s_addc_u32 s101, vcc_hi, 0
	global_load_lds_dwordx4 v182, s[100:101]
	s_add_i32 m0, s12, 0x2000
	s_add_u32 s12, vcc_lo, 0x80080
	s_addc_u32 s13, vcc_hi, 0
	s_add_i32 s19, s51, s37
	global_load_lds_dwordx4 v192, s[100:101]
	s_mov_b32 m0, s19
	s_nop 0
	global_load_lds_dwordx4 v182, s[12:13]
	s_add_i32 m0, s19, 0x2000
	s_nop 0
	global_load_lds_dwordx4 v192, s[12:13]
	s_mov_b32 m0, s45
	s_nop 0
	s_add_u32 s100, s40, 0x80
	s_addc_u32 s101, s41, 0
	global_load_lds_dwordx4 v188, s[100:101]
	s_mov_b32 m0, s24
	s_nop 0
	global_load_lds_dwordx4 v190, s[100:101]
	s_waitcnt vmcnt(8)
	s_waitcnt lgkmcnt(0)
	s_setprio 1
	s_barrier
	v_mfma_f32_16x16x32_bf16 v[30:33], v[66:69], v[162:165], v[30:33]
	v_mfma_f32_16x16x32_bf16 v[22:25], v[82:85], v[162:165], v[22:25]
	v_mfma_f32_16x16x32_bf16 v[26:29], v[66:69], v[170:173], v[26:29]
	v_mfma_f32_16x16x32_bf16 v[18:21], v[82:85], v[170:173], v[18:21]
	v_mfma_f32_16x16x32_bf16 v[62:65], v[66:69], v[178:181], v[62:65]
	v_mfma_f32_16x16x32_bf16 v[54:57], v[82:85], v[178:181], v[54:57]
	v_mfma_f32_16x16x32_bf16 v[58:61], v[66:69], v[220:223], v[58:61]
	v_mfma_f32_16x16x32_bf16 v[50:53], v[82:85], v[220:223], v[50:53]
	v_mfma_f32_16x16x32_bf16 v[30:33], v[70:73], v[166:169], v[30:33]
	v_mfma_f32_16x16x32_bf16 v[22:25], v[142:145], v[166:169], v[22:25]
	v_mfma_f32_16x16x32_bf16 v[26:29], v[70:73], v[174:177], v[26:29]
	v_mfma_f32_16x16x32_bf16 v[18:21], v[142:145], v[174:177], v[18:21]
	v_mfma_f32_16x16x32_bf16 v[62:65], v[70:73], v[184:187], v[62:65]
	v_mfma_f32_16x16x32_bf16 v[54:57], v[142:145], v[184:187], v[54:57]
	v_mfma_f32_16x16x32_bf16 v[58:61], v[70:73], v[224:227], v[58:61]
	v_mfma_f32_16x16x32_bf16 v[50:53], v[142:145], v[224:227], v[50:53]
	v_mfma_f32_16x16x32_bf16 v[14:17], v[146:149], v[162:165], v[14:17]
	v_mfma_f32_16x16x32_bf16 v[6:9], v[154:157], v[162:165], v[6:9]
	v_mfma_f32_16x16x32_bf16 v[10:13], v[146:149], v[170:173], v[10:13]
	v_mfma_f32_16x16x32_bf16 v[2:5], v[154:157], v[170:173], v[2:5]
	v_mfma_f32_16x16x32_bf16 v[46:49], v[146:149], v[178:181], v[46:49]
	v_mfma_f32_16x16x32_bf16 v[34:37], v[154:157], v[178:181], v[34:37]
	v_mfma_f32_16x16x32_bf16 v[38:41], v[146:149], v[220:223], v[38:41]
	v_mfma_f32_16x16x32_bf16 v[42:45], v[154:157], v[220:223], v[42:45]
	v_mfma_f32_16x16x32_bf16 v[14:17], v[150:153], v[166:169], v[14:17]
	v_mfma_f32_16x16x32_bf16 v[6:9], v[158:161], v[166:169], v[6:9]
	v_mfma_f32_16x16x32_bf16 v[10:13], v[150:153], v[174:177], v[10:13]
	v_mfma_f32_16x16x32_bf16 v[2:5], v[158:161], v[174:177], v[2:5]
	v_mfma_f32_16x16x32_bf16 v[46:49], v[150:153], v[184:187], v[46:49]
	v_mfma_f32_16x16x32_bf16 v[34:37], v[158:161], v[184:187], v[34:37]
	v_mfma_f32_16x16x32_bf16 v[38:41], v[150:153], v[224:227], v[38:41]
	v_mfma_f32_16x16x32_bf16 v[42:45], v[158:161], v[224:227], v[42:45]
	s_barrier
	s_setprio 0
	s_add_i32 s0, s0, 2
	s_add_u32 s66, s66, 0x100
	s_addc_u32 s67, s67, 0
	s_cmp_gt_u32 s0, 29
	s_mov_b64 s[12:13], s[96:97]
	s_cbranch_scc0 .LBB0_1327
	s_and_b64 vcc, exec, s[78:79]
	s_cbranch_vccz .LBB0_1330
	s_barrier

; #define PG8_STAGE(bufoff, gbase, voff) do { _Pragma("unroll") for (int _i = 0; _i < 2; ++_i) \
;         __builtin_amdgcn_global_load_lds((const unsigned*)((const char*)(gbase) + (voff)[_i]), (PG8_LAS unsigned*)(lds + (bufoff) + ldsw + _i * 8192), 16, 0, 0); } while (0)
; #define PG8_LDA(dst, b, h) do { _Pragma("unroll") for (int m = 0; m < 4; ++m) _Pragma("unroll") for (int k = 0; k < 2; ++k) dst[m][k] = *(const PG8_LAS bf16x8*)(lds + PG8_SA(b, h) + aoff + m * 2048 + k * 1024); } while (0)
; #define PG8_LDB(dst, b, h) do { _Pragma("unroll") for (int n = 0; n < 2; ++n) _Pragma("unroll") for (int k = 0; k < 2; ++k) dst[n][k] = *(const PG8_LAS bf16x8*)(lds + PG8_SB(b, h) + boff + n * 2048 + k * 1024); } while (0)
; #define PG8_WAIT_L(n) asm volatile("s_waitcnt lgkmcnt(" #n ")" ::: "memory")
; #define PG8_WAIT_V_SEL(sel) asm volatile("s_cmp_eq_u32 %0, 0\n\ts_cbranch_scc1 .Lw8_%=\n\ts_waitcnt vmcnt(22)\n\ts_branch .Lwd_%=\n.Lw8_%=:\n\ts_waitcnt vmcnt(8)\n.Lwd_%=:" :: "s"(sel) : "memory", "scc")
; #define PG8_BAR __builtin_amdgcn_s_barrier()
; #define PG8_SCHED __builtin_amdgcn_sched_barrier(0)
;     ...
;             PG8_LDB(B0, 0, 0); PG8_LDB(B1, 0, 1); PG8_SCHED; PG8_LDA(At, 0, 0); PG8_STAGE(PG8_SA(1, 1), a1 + hstep, voffA);
;             PG8_WAIT_V_SEL(relax);
;             PG8_WAIT_L(0); PG8_BAR; PG8_MMA(0, 0, At, B0); PG8_MMA(0, 1, At, B1); PG8_BAR; PG8_SCHED;
;             PG8_LDA(At, 0, 1); PG8_STAGE(PG8_SB(0, 0), b2, voffB); PG8_STAGE(PG8_SB(0, 1), b2 + hstep, voffB); PG8_STAGE(PG8_SA(0, 0), a2, voffA);
;             PG8_WAIT_V_SEL(relax);
;             PG8_WAIT_L(0); PG8_BAR; PG8_MMA(1, 0, At, B0); PG8_MMA(1, 1, At, B1); PG8_BAR; PG8_SCHED;
.LBB0_1648:
	s_add_u32 s10, s8, 0x100
	s_addc_u32 s11, s9, 0
	s_add_i32 s46, 0, 0x10000
	s_cmpk_eq_i32 s45, 0x52
	s_cselect_b32 s41, s1, s11
	s_cselect_b32 s40, s0, s10
	s_cselect_b32 s81, s79, s44
	s_cselect_b32 s80, s78, s37
	s_add_i32 s47, 0, 0x14000
	v_add_u32_e32 v78, s46, v243
	v_add_u32_e32 v158, s47, v243
	ds_read_b128 v[58:61], v78
	ds_read_b128 v[62:65], v78 offset:1024
	ds_read_b128 v[74:77], v78 offset:2048
	ds_read_b128 v[78:81], v78 offset:3072
	ds_read_b128 v[130:133], v158
	ds_read_b128 v[142:145], v158 offset:1024
	ds_read_b128 v[154:157], v158 offset:2048
	ds_read_b128 v[158:161], v158 offset:3072
	s_add_i32 m0, s91, 0xc000
	ds_read_b128 v[162:165], v246
	ds_read_b128 v[166:169], v246 offset:1024
	ds_read_b128 v[170:173], v246 offset:2048
	ds_read_b128 v[174:177], v246 offset:3072
	ds_read_b128 v[184:187], v246 offset:4096
	ds_read_b128 v[194:197], v246 offset:5120
	ds_read_b128 v[198:201], v246 offset:6144
	ds_read_b128 v[202:205], v246 offset:7168
	global_load_lds_dwordx4 v190, s[8:9]
	s_add_i32 m0, s91, 0xe000
	s_nop 0
	global_load_lds_dwordx4 v192, s[8:9]
	s_waitcnt vmcnt(8)
	s_waitcnt lgkmcnt(0)
	s_setprio 1
	s_barrier
	v_mfma_f32_16x16x32_bf16 v[150:153], v[58:61], v[162:165], v[150:153]
	v_mfma_f32_16x16x32_bf16 v[146:149], v[74:77], v[162:165], v[146:149]
	v_mfma_f32_16x16x32_bf16 v[126:129], v[58:61], v[170:173], v[126:129]
	v_mfma_f32_16x16x32_bf16 v[122:125], v[74:77], v[170:173], v[122:125]
	v_mfma_f32_16x16x32_bf16 v[110:113], v[58:61], v[184:187], v[110:113]
	v_mfma_f32_16x16x32_bf16 v[106:109], v[74:77], v[184:187], v[106:109]
	v_mfma_f32_16x16x32_bf16 v[94:97], v[58:61], v[198:201], v[94:97]
	v_mfma_f32_16x16x32_bf16 v[90:93], v[74:77], v[198:201], v[90:93]
	v_mfma_f32_16x16x32_bf16 v[150:153], v[62:65], v[166:169], v[150:153]
	v_mfma_f32_16x16x32_bf16 v[146:149], v[78:81], v[166:169], v[146:149]
	v_mfma_f32_16x16x32_bf16 v[126:129], v[62:65], v[174:177], v[126:129]
	v_mfma_f32_16x16x32_bf16 v[122:125], v[78:81], v[174:177], v[122:125]
	v_mfma_f32_16x16x32_bf16 v[110:113], v[62:65], v[194:197], v[110:113]
	v_mfma_f32_16x16x32_bf16 v[106:109], v[78:81], v[194:197], v[106:109]
	v_mfma_f32_16x16x32_bf16 v[94:97], v[62:65], v[202:205], v[94:97]
	v_mfma_f32_16x16x32_bf16 v[90:93], v[78:81], v[202:205], v[90:93]
	v_mfma_f32_16x16x32_bf16 v[138:141], v[130:133], v[162:165], v[138:141]
	v_mfma_f32_16x16x32_bf16 v[134:137], v[154:157], v[162:165], v[134:137]
	v_mfma_f32_16x16x32_bf16 v[118:121], v[130:133], v[170:173], v[118:121]
	v_mfma_f32_16x16x32_bf16 v[114:117], v[154:157], v[170:173], v[114:117]
	v_mfma_f32_16x16x32_bf16 v[102:105], v[130:133], v[184:187], v[102:105]
	v_mfma_f32_16x16x32_bf16 v[98:101], v[154:157], v[184:187], v[98:101]
	v_mfma_f32_16x16x32_bf16 v[86:89], v[130:133], v[198:201], v[86:89]
	v_mfma_f32_16x16x32_bf16 v[82:85], v[154:157], v[198:201], v[82:85]
	v_mfma_f32_16x16x32_bf16 v[138:141], v[142:145], v[166:169], v[138:141]
	v_mfma_f32_16x16x32_bf16 v[134:137], v[158:161], v[166:169], v[134:137]
	v_mfma_f32_16x16x32_bf16 v[118:121], v[142:145], v[174:177], v[118:121]
	v_mfma_f32_16x16x32_bf16 v[114:117], v[158:161], v[174:177], v[114:117]
	v_mfma_f32_16x16x32_bf16 v[102:105], v[142:145], v[194:197], v[102:105]
	v_mfma_f32_16x16x32_bf16 v[98:101], v[158:161], v[194:197], v[98:101]
	v_mfma_f32_16x16x32_bf16 v[86:89], v[142:145], v[202:205], v[86:89]
	v_mfma_f32_16x16x32_bf16 v[82:85], v[158:161], v[202:205], v[82:85]
	s_barrier
	s_setprio 0
	s_add_i32 s8, s46, s90
	s_mov_b32 m0, s8
	ds_read_b128 v[162:165], v246 offset:16384
	ds_read_b128 v[166:169], v246 offset:17408
	ds_read_b128 v[170:173], v246 offset:18432
	ds_read_b128 v[174:177], v246 offset:19456
	ds_read_b128 v[184:187], v246 offset:20480
	ds_read_b128 v[194:197], v246 offset:21504
	ds_read_b128 v[198:201], v246 offset:22528
	ds_read_b128 v[202:205], v246 offset:23552
	global_load_lds_dwordx4 v182, s[80:81]
	s_add_i32 m0, s8, 0x2000
	s_add_u32 s8, s80, 0x158000
	s_addc_u32 s9, s81, 0
	s_add_i32 s46, s47, s90
	global_load_lds_dwordx4 v188, s[80:81]
	s_mov_b32 m0, s46
	v_lshl_add_u64 v[212:213], s[40:41], 0, v[180:181]
	global_load_lds_dwordx4 v182, s[8:9]
	s_add_i32 m0, s46, 0x2000
	s_nop 0
	global_load_lds_dwordx4 v188, s[8:9]
	v_lshl_add_u64 v[210:211], s[40:41], 0, v[178:179]
	s_mov_b32 m0, s91
	s_nop 0
	global_load_lds_dwordx4 v178, s[40:41]
	s_mov_b32 m0, s92
	s_nop 0
	global_load_lds_dwordx4 v180, s[40:41]
	s_waitcnt vmcnt(8)
	s_waitcnt lgkmcnt(0)
	s_setprio 1
	s_barrier
	v_mfma_f32_16x16x32_bf16 v[70:73], v[58:61], v[162:165], v[70:73]
	v_mfma_f32_16x16x32_bf16 v[66:69], v[74:77], v[162:165], v[66:69]
	v_mfma_f32_16x16x32_bf16 v[46:49], v[58:61], v[170:173], v[46:49]
	v_mfma_f32_16x16x32_bf16 v[42:45], v[74:77], v[170:173], v[42:45]
	v_mfma_f32_16x16x32_bf16 v[30:33], v[58:61], v[184:187], v[30:33]
	v_mfma_f32_16x16x32_bf16 v[26:29], v[74:77], v[184:187], v[26:29]
	v_mfma_f32_16x16x32_bf16 v[14:17], v[58:61], v[198:201], v[14:17]
	v_mfma_f32_16x16x32_bf16 v[10:13], v[74:77], v[198:201], v[10:13]
	v_mfma_f32_16x16x32_bf16 v[70:73], v[62:65], v[166:169], v[70:73]
	v_mfma_f32_16x16x32_bf16 v[66:69], v[78:81], v[166:169], v[66:69]
	v_mfma_f32_16x16x32_bf16 v[46:49], v[62:65], v[174:177], v[46:49]
	v_mfma_f32_16x16x32_bf16 v[42:45], v[78:81], v[174:177], v[42:45]
	v_mfma_f32_16x16x32_bf16 v[30:33], v[62:65], v[194:197], v[30:33]
	v_mfma_f32_16x16x32_bf16 v[26:29], v[78:81], v[194:197], v[26:29]
	v_mfma_f32_16x16x32_bf16 v[14:17], v[62:65], v[202:205], v[14:17]
	v_mfma_f32_16x16x32_bf16 v[10:13], v[78:81], v[202:205], v[10:13]
	v_mfma_f32_16x16x32_bf16 v[54:57], v[130:133], v[162:165], v[54:57]
	v_mfma_f32_16x16x32_bf16 v[50:53], v[154:157], v[162:165], v[50:53]
	v_mfma_f32_16x16x32_bf16 v[38:41], v[130:133], v[170:173], v[38:41]
	v_mfma_f32_16x16x32_bf16 v[34:37], v[154:157], v[170:173], v[34:37]
	v_mfma_f32_16x16x32_bf16 v[22:25], v[130:133], v[184:187], v[22:25]
	v_mfma_f32_16x16x32_bf16 v[18:21], v[154:157], v[184:187], v[18:21]
	v_mfma_f32_16x16x32_bf16 v[6:9], v[130:133], v[198:201], v[6:9]
	v_mfma_f32_16x16x32_bf16 v[2:5], v[154:157], v[198:201], v[2:5]
	v_mfma_f32_16x16x32_bf16 v[54:57], v[142:145], v[166:169], v[54:57]
	v_mfma_f32_16x16x32_bf16 v[50:53], v[158:161], v[166:169], v[50:53]
	v_mfma_f32_16x16x32_bf16 v[38:41], v[142:145], v[174:177], v[38:41]
	v_mfma_f32_16x16x32_bf16 v[34:37], v[158:161], v[174:177], v[34:37]
	v_mfma_f32_16x16x32_bf16 v[22:25], v[142:145], v[194:197], v[22:25]
	v_mfma_f32_16x16x32_bf16 v[18:21], v[158:161], v[194:197], v[18:21]
	v_mfma_f32_16x16x32_bf16 v[6:9], v[142:145], v[202:205], v[6:9]
	v_mfma_f32_16x16x32_bf16 v[2:5], v[158:161], v[202:205], v[2:5]
	s_barrier
; #define PG8_STAGE(bufoff, gbase, voff) do { _Pragma("unroll") for (int _i = 0; _i < 2; ++_i) \
;         __builtin_amdgcn_global_load_lds((const unsigned*)((const char*)(gbase) + (voff)[_i]), (PG8_LAS unsigned*)(lds + (bufoff) + ldsw + _i * 8192), 16, 0, 0); } while (0)
; #define PG8_LDA(dst, b, h) do { _Pragma("unroll") for (int m = 0; m < 4; ++m) _Pragma("unroll") for (int k = 0; k < 2; ++k) dst[m][k] = *(const PG8_LAS bf16x8*)(lds + PG8_SA(b, h) + aoff + m * 2048 + k * 1024); } while (0)
; #define PG8_LDB(dst, b, h) do { _Pragma("unroll") for (int n = 0; n < 2; ++n) _Pragma("unroll") for (int k = 0; k < 2; ++k) dst[n][k] = *(const PG8_LAS bf16x8*)(lds + PG8_SB(b, h) + boff + n * 2048 + k * 1024); } while (0)
; #define PG8_WAIT_V(n) asm volatile("s_waitcnt vmcnt(" #n ")" ::: "memory")
; #define PG8_WAIT_L(n) asm volatile("s_waitcnt lgkmcnt(" #n ")" ::: "memory")
; #define PG8_BAR __builtin_amdgcn_s_barrier()
; #define PG8_SCHED __builtin_amdgcn_sched_barrier(0)
;     ...
;             PG8_LDB(B0, 1, 0); PG8_LDB(B1, 1, 1); PG8_SCHED; PG8_LDA(At, 1, 0); PG8_STAGE(PG8_SA(0, 1), a2 + hstep, voffA);
;             PG8_WAIT_V(8); PG8_WAIT_L(0); PG8_BAR; PG8_MMA(0, 0, At, B0); PG8_MMA(0, 1, At, B1); PG8_BAR; PG8_SCHED;
;             PG8_LDA(At, 1, 1); PG8_STAGE(PG8_SB(1, 0), b3, voffB); PG8_STAGE(PG8_SB(1, 1), b3 + hstep, voffB); PG8_STAGE(PG8_SA(1, 0), a3, voffA);
;             PG8_WAIT_V(8); PG8_WAIT_L(0); PG8_BAR; PG8_MMA(1, 0, At, B0); PG8_MMA(1, 1, At, B1); PG8_BAR; PG8_SCHED;
	s_setprio 0
	s_add_i32 s46, 0, 0x18000
	s_add_i32 s47, 0, 0x1c000
	v_add_u32_e32 v78, s46, v243
	v_add_u32_e32 v158, s47, v243
	ds_read_b128 v[58:61], v78
	ds_read_b128 v[62:65], v78 offset:1024
	ds_read_b128 v[74:77], v78 offset:2048
	ds_read_b128 v[78:81], v78 offset:3072
	ds_read_b128 v[130:133], v158
	ds_read_b128 v[142:145], v158 offset:1024
	ds_read_b128 v[154:157], v158 offset:2048
	ds_read_b128 v[158:161], v158 offset:3072
	s_add_u32 s8, s40, 0x158000
	s_addc_u32 s9, s41, 0
	s_mov_b32 m0, s93
	ds_read_b128 v[162:165], v246 offset:32768
	ds_read_b128 v[166:169], v246 offset:33792
	ds_read_b128 v[170:173], v246 offset:34816
	ds_read_b128 v[174:177], v246 offset:35840
	ds_read_b128 v[184:187], v246 offset:36864
	ds_read_b128 v[194:197], v246 offset:37888
	ds_read_b128 v[198:201], v246 offset:38912
	ds_read_b128 v[202:205], v246 offset:39936
	global_load_lds_dwordx4 v178, s[8:9]
	s_mov_b32 m0, s94
	s_nop 0
	global_load_lds_dwordx4 v180, s[8:9]
	s_waitcnt vmcnt(8)
	s_waitcnt lgkmcnt(0)
	s_setprio 1
	s_barrier
	v_mfma_f32_16x16x32_bf16 v[150:153], v[58:61], v[162:165], v[150:153]
	v_mfma_f32_16x16x32_bf16 v[146:149], v[74:77], v[162:165], v[146:149]
	v_mfma_f32_16x16x32_bf16 v[126:129], v[58:61], v[170:173], v[126:129]
	v_mfma_f32_16x16x32_bf16 v[122:125], v[74:77], v[170:173], v[122:125]
	v_mfma_f32_16x16x32_bf16 v[110:113], v[58:61], v[184:187], v[110:113]
	v_mfma_f32_16x16x32_bf16 v[106:109], v[74:77], v[184:187], v[106:109]
	v_mfma_f32_16x16x32_bf16 v[94:97], v[58:61], v[198:201], v[94:97]
	v_mfma_f32_16x16x32_bf16 v[90:93], v[74:77], v[198:201], v[90:93]
	v_mfma_f32_16x16x32_bf16 v[150:153], v[62:65], v[166:169], v[150:153]
	v_mfma_f32_16x16x32_bf16 v[146:149], v[78:81], v[166:169], v[146:149]
	v_mfma_f32_16x16x32_bf16 v[126:129], v[62:65], v[174:177], v[126:129]
	v_mfma_f32_16x16x32_bf16 v[122:125], v[78:81], v[174:177], v[122:125]
	v_mfma_f32_16x16x32_bf16 v[110:113], v[62:65], v[194:197], v[110:113]
	v_mfma_f32_16x16x32_bf16 v[106:109], v[78:81], v[194:197], v[106:109]
	v_mfma_f32_16x16x32_bf16 v[94:97], v[62:65], v[202:205], v[94:97]
	v_mfma_f32_16x16x32_bf16 v[90:93], v[78:81], v[202:205], v[90:93]
	v_mfma_f32_16x16x32_bf16 v[138:141], v[130:133], v[162:165], v[138:141]
	v_mfma_f32_16x16x32_bf16 v[134:137], v[154:157], v[162:165], v[134:137]
	v_mfma_f32_16x16x32_bf16 v[118:121], v[130:133], v[170:173], v[118:121]
	v_mfma_f32_16x16x32_bf16 v[114:117], v[154:157], v[170:173], v[114:117]
	v_mfma_f32_16x16x32_bf16 v[102:105], v[130:133], v[184:187], v[102:105]
	v_mfma_f32_16x16x32_bf16 v[98:101], v[154:157], v[184:187], v[98:101]
	v_mfma_f32_16x16x32_bf16 v[86:89], v[130:133], v[198:201], v[86:89]
	v_mfma_f32_16x16x32_bf16 v[82:85], v[154:157], v[198:201], v[82:85]
	v_mfma_f32_16x16x32_bf16 v[138:141], v[142:145], v[166:169], v[138:141]
	v_mfma_f32_16x16x32_bf16 v[134:137], v[158:161], v[166:169], v[134:137]
	v_mfma_f32_16x16x32_bf16 v[118:121], v[142:145], v[174:177], v[118:121]
	v_mfma_f32_16x16x32_bf16 v[114:117], v[158:161], v[174:177], v[114:117]
	v_mfma_f32_16x16x32_bf16 v[102:105], v[142:145], v[194:197], v[102:105]
	v_mfma_f32_16x16x32_bf16 v[98:101], v[158:161], v[194:197], v[98:101]
	v_mfma_f32_16x16x32_bf16 v[86:89], v[142:145], v[202:205], v[86:89]
	v_mfma_f32_16x16x32_bf16 v[82:85], v[158:161], v[202:205], v[82:85]
	s_barrier
	s_setprio 0
	s_add_i32 s8, s46, s90
	s_mov_b32 m0, s8
	ds_read_b128 v[162:165], v246 offset:49152
	ds_read_b128 v[166:169], v246 offset:50176
	ds_read_b128 v[170:173], v246 offset:51200
	ds_read_b128 v[174:177], v246 offset:52224
	ds_read_b128 v[184:187], v246 offset:53248
	ds_read_b128 v[194:197], v246 offset:54272
	ds_read_b128 v[198:201], v246 offset:55296
	ds_read_b128 v[202:205], v246 offset:56320
	s_add_u32 s100, s80, 0x80
	s_addc_u32 s101, s81, 0
	global_load_lds_dwordx4 v182, s[100:101]
	s_add_i32 m0, s8, 0x2000
	s_add_u32 s8, s80, 0x158080
	s_addc_u32 s9, s81, 0
	s_add_i32 s40, s47, s90
	global_load_lds_dwordx4 v188, s[100:101]
	s_mov_b32 m0, s40
	s_nop 0
	global_load_lds_dwordx4 v182, s[8:9]
	s_add_i32 m0, s40, 0x2000
	s_nop 0
	global_load_lds_dwordx4 v188, s[8:9]
	v_lshl_add_u64 v[206:207], v[210:211], 0, s[28:29]
	s_mov_b32 m0, s31
	s_nop 0
	global_load_lds_dwordx4 v[206:207], off
	v_lshl_add_u64 v[206:207], v[212:213], 0, s[28:29]
	s_mov_b32 m0, s56
	s_nop 0
	global_load_lds_dwordx4 v[206:207], off
	s_waitcnt vmcnt(8)
	s_waitcnt lgkmcnt(0)
	s_setprio 1
	s_barrier
	v_mfma_f32_16x16x32_bf16 v[70:73], v[58:61], v[162:165], v[70:73]
	v_mfma_f32_16x16x32_bf16 v[66:69], v[74:77], v[162:165], v[66:69]
	v_mfma_f32_16x16x32_bf16 v[46:49], v[58:61], v[170:173], v[46:49]
	v_mfma_f32_16x16x32_bf16 v[42:45], v[74:77], v[170:173], v[42:45]
	v_mfma_f32_16x16x32_bf16 v[30:33], v[58:61], v[184:187], v[30:33]
	v_mfma_f32_16x16x32_bf16 v[26:29], v[74:77], v[184:187], v[26:29]
	v_mfma_f32_16x16x32_bf16 v[14:17], v[58:61], v[198:201], v[14:17]
	v_mfma_f32_16x16x32_bf16 v[10:13], v[74:77], v[198:201], v[10:13]
	v_mfma_f32_16x16x32_bf16 v[70:73], v[62:65], v[166:169], v[70:73]
	v_mfma_f32_16x16x32_bf16 v[66:69], v[78:81], v[166:169], v[66:69]
	v_mfma_f32_16x16x32_bf16 v[46:49], v[62:65], v[174:177], v[46:49]
	v_mfma_f32_16x16x32_bf16 v[42:45], v[78:81], v[174:177], v[42:45]
	v_mfma_f32_16x16x32_bf16 v[30:33], v[62:65], v[194:197], v[30:33]
	v_mfma_f32_16x16x32_bf16 v[26:29], v[78:81], v[194:197], v[26:29]
	v_mfma_f32_16x16x32_bf16 v[14:17], v[62:65], v[202:205], v[14:17]
	v_mfma_f32_16x16x32_bf16 v[10:13], v[78:81], v[202:205], v[10:13]
	v_mfma_f32_16x16x32_bf16 v[54:57], v[130:133], v[162:165], v[54:57]
	v_mfma_f32_16x16x32_bf16 v[50:53], v[154:157], v[162:165], v[50:53]
	v_mfma_f32_16x16x32_bf16 v[38:41], v[130:133], v[170:173], v[38:41]
	v_mfma_f32_16x16x32_bf16 v[34:37], v[154:157], v[170:173], v[34:37]
	v_mfma_f32_16x16x32_bf16 v[22:25], v[130:133], v[184:187], v[22:25]
	v_mfma_f32_16x16x32_bf16 v[18:21], v[154:157], v[184:187], v[18:21]
	v_mfma_f32_16x16x32_bf16 v[6:9], v[130:133], v[198:201], v[6:9]
	v_mfma_f32_16x16x32_bf16 v[2:5], v[154:157], v[198:201], v[2:5]
	v_mfma_f32_16x16x32_bf16 v[54:57], v[142:145], v[166:169], v[54:57]
	v_mfma_f32_16x16x32_bf16 v[50:53], v[158:161], v[166:169], v[50:53]
	v_mfma_f32_16x16x32_bf16 v[38:41], v[142:145], v[174:177], v[38:41]
	v_mfma_f32_16x16x32_bf16 v[34:37], v[158:161], v[174:177], v[34:37]
	v_mfma_f32_16x16x32_bf16 v[22:25], v[142:145], v[194:197], v[22:25]
	v_mfma_f32_16x16x32_bf16 v[18:21], v[158:161], v[194:197], v[18:21]
	v_mfma_f32_16x16x32_bf16 v[6:9], v[142:145], v[202:205], v[6:9]
	v_mfma_f32_16x16x32_bf16 v[2:5], v[158:161], v[202:205], v[2:5]
	s_barrier
	s_setprio 0
	s_add_i32 s45, s45, 2
	s_add_u32 s37, s37, 0x100
	s_addc_u32 s44, s44, 0
	s_cmpk_gt_u32 s45, 0x53
	s_mov_b64 s[8:9], s[10:11]
	s_cbranch_scc0 .LBB0_1648
	s_and_b64 vcc, exec, s[76:77]
	s_cbranch_vccz .LBB0_1651
	s_barrier

; __global__ void __launch_bounds__(NWAVES * 64, 2) mega_fwd(Args args) {
	.amdhsa_kernel _Z8mega_fwd4Args
		.amdhsa_group_segment_fixed_size 0
		.amdhsa_private_segment_fixed_size 0
		.amdhsa_kernarg_size 432
		.amdhsa_user_sgpr_count 2
		.amdhsa_user_sgpr_dispatch_ptr 0
		.amdhsa_user_sgpr_queue_ptr 0
		.amdhsa_user_sgpr_kernarg_segment_ptr 1
		.amdhsa_user_sgpr_dispatch_id 0
		.amdhsa_user_sgpr_kernarg_preload_length 0
		.amdhsa_user_sgpr_kernarg_preload_offset 0
		.amdhsa_user_sgpr_private_segment_size 0
		.amdhsa_uses_dynamic_stack 0
		.amdhsa_enable_private_segment 0
		.amdhsa_system_sgpr_workgroup_id_x 1
		.amdhsa_system_sgpr_workgroup_id_y 0
		.amdhsa_system_sgpr_workgroup_id_z 0
		.amdhsa_system_sgpr_workgroup_info 0
		.amdhsa_system_vgpr_workitem_id 0
		.amdhsa_next_free_vgpr 256
		.amdhsa_next_free_sgpr 102
		.amdhsa_accum_offset 256
		.amdhsa_reserve_vcc 1
		.amdhsa_float_round_mode_32 0
		.amdhsa_float_round_mode_16_64 0
		.amdhsa_float_denorm_mode_32 3
		.amdhsa_float_denorm_mode_16_64 3
		.amdhsa_dx10_clamp 1
		.amdhsa_ieee_mode 1
		.amdhsa_fp16_overflow 0
		.amdhsa_tg_split 0
		.amdhsa_exception_fp_ieee_invalid_op 0
		.amdhsa_exception_fp_denorm_src 0
		.amdhsa_exception_fp_ieee_div_zero 0
		.amdhsa_exception_fp_ieee_overflow 0
		.amdhsa_exception_fp_ieee_underflow 0
		.amdhsa_exception_fp_ieee_inexact 0
		.amdhsa_exception_int_div_zero 0
	.end_amdhsa_kernel

; __global__ void __launch_bounds__(NWAVES * 64, 2) mega_fwd(Args args) {
amdhsa.kernels:
  - .agpr_count:     0
    .args:
      - .offset:         0
        .size:           176
        .value_kind:     by_value
      - .offset:         176
        .size:           4
        .value_kind:     hidden_block_count_x
      - .offset:         180
        .size:           4
        .value_kind:     hidden_block_count_y
      - .offset:         184
        .size:           4
        .value_kind:     hidden_block_count_z
      - .offset:         188
        .size:           2
        .value_kind:     hidden_group_size_x
      - .offset:         190
        .size:           2
        .value_kind:     hidden_group_size_y
      - .offset:         192
        .size:           2
        .value_kind:     hidden_group_size_z
      - .offset:         194
        .size:           2
        .value_kind:     hidden_remainder_x
      - .offset:         196
        .size:           2
        .value_kind:     hidden_remainder_y
      - .offset:         198
        .size:           2
        .value_kind:     hidden_remainder_z
      - .offset:         216
        .size:           8
        .value_kind:     hidden_global_offset_x
      - .offset:         224
        .size:           8
        .value_kind:     hidden_global_offset_y
      - .offset:         232
        .size:           8
        .value_kind:     hidden_global_offset_z
      - .offset:         240
        .size:           2
        .value_kind:     hidden_grid_dims
      - .offset:         296
        .size:           4
        .value_kind:     hidden_dynamic_lds_size
    .group_segment_fixed_size: 0
    .kernarg_segment_align: 8
    .kernarg_segment_size: 432
    .language:       OpenCL C
    .language_version:
      - 2
      - 0
    .max_flat_workgroup_size: 512
    .name:           _Z8mega_fwd4Args
    .private_segment_fixed_size: 0
    .sgpr_count:     108
    .sgpr_spill_count: 55
    .symbol:         _Z8mega_fwd4Args.kd
    .uniform_work_group_size: 1
    .uses_dynamic_stack: false
    .vgpr_count:     256
    .vgpr_spill_count: 0
    .wavefront_size: 64
